# GEMM K-loops: counter/pointer updates and exit compare moved above the closing barrier (back edge = branch only); redundant s_setprio pair and duplicate lgkmcnt(0) behind the barrier removed
# baseline (speedup 1.0000x reference)
.LBB0_397:
	s_add_u32 s42, s24, 0xfffc0080
	s_addc_u32 s43, s25, -1
	s_add_i32 s66, 0, 0x10000
	s_cmp_eq_u32 s65, 12
	s_cselect_b32 vcc_hi, s23, s43
	s_cselect_b32 vcc_lo, s26, s42
	s_cselect_b32 s43, s27, s45
	s_cselect_b32 s42, s28, s29
	s_add_i32 s83, 0, 0x14000
	v_add_u32_e32 v76, s66, v185
	v_add_u32_e32 v154, s83, v185
	ds_read_b128 v[64:67], v76
	ds_read_b128 v[68:71], v76 offset:1024
	ds_read_b128 v[72:75], v76 offset:2048
	ds_read_b128 v[76:79], v76 offset:3072
	ds_read_b128 v[144:147], v154
	ds_read_b128 v[148:151], v154 offset:1024
	ds_read_b128 v[172:175], v154 offset:2048
	ds_read_b128 v[176:179], v154 offset:3072
	v_lshl_add_u64 v[224:225], s[24:25], 0, v[168:169]
	s_add_i32 m0, s33, 0xc000
	ds_read_b128 v[180:183], v194
	ds_read_b128 v[196:199], v194 offset:1024
	ds_read_b128 v[200:203], v194 offset:2048
	ds_read_b128 v[204:207], v194 offset:3072
	ds_read_b128 v[208:211], v194 offset:4096
	ds_read_b128 v[212:215], v194 offset:5120
	ds_read_b128 v[216:219], v194 offset:6144
	ds_read_b128 v[220:223], v194 offset:7168
	global_load_lds_dwordx4 v[224:225], off
	v_lshl_add_u64 v[224:225], s[24:25], 0, v[170:171]
	s_add_i32 m0, s33, 0xe000
	s_nop 0
	global_load_lds_dwordx4 v[224:225], off
	s_waitcnt vmcnt(8)
	s_waitcnt lgkmcnt(0)
	s_barrier
	s_setprio 1
	v_mfma_f32_16x16x32_bf16 v[140:143], v[64:67], v[180:183], v[140:143]
	v_mfma_f32_16x16x32_bf16 v[136:139], v[72:75], v[180:183], v[136:139]
	v_mfma_f32_16x16x32_bf16 v[124:127], v[64:67], v[200:203], v[124:127]
	v_mfma_f32_16x16x32_bf16 v[120:123], v[72:75], v[200:203], v[120:123]
	v_mfma_f32_16x16x32_bf16 v[108:111], v[64:67], v[208:211], v[108:111]
	v_mfma_f32_16x16x32_bf16 v[104:107], v[72:75], v[208:211], v[104:107]
	v_mfma_f32_16x16x32_bf16 v[92:95], v[64:67], v[216:219], v[92:95]
	v_mfma_f32_16x16x32_bf16 v[88:91], v[72:75], v[216:219], v[88:91]
	v_mfma_f32_16x16x32_bf16 v[140:143], v[68:71], v[196:199], v[140:143]
	v_mfma_f32_16x16x32_bf16 v[136:139], v[76:79], v[196:199], v[136:139]
	v_mfma_f32_16x16x32_bf16 v[124:127], v[68:71], v[204:207], v[124:127]
	v_mfma_f32_16x16x32_bf16 v[120:123], v[76:79], v[204:207], v[120:123]
	v_mfma_f32_16x16x32_bf16 v[108:111], v[68:71], v[212:215], v[108:111]
	v_mfma_f32_16x16x32_bf16 v[104:107], v[76:79], v[212:215], v[104:107]
	v_mfma_f32_16x16x32_bf16 v[92:95], v[68:71], v[220:223], v[92:95]
	v_mfma_f32_16x16x32_bf16 v[88:91], v[76:79], v[220:223], v[88:91]
	v_mfma_f32_16x16x32_bf16 v[132:135], v[144:147], v[180:183], v[132:135]
	v_mfma_f32_16x16x32_bf16 v[128:131], v[172:175], v[180:183], v[128:131]
	v_mfma_f32_16x16x32_bf16 v[116:119], v[144:147], v[200:203], v[116:119]
	v_mfma_f32_16x16x32_bf16 v[112:115], v[172:175], v[200:203], v[112:115]
	v_mfma_f32_16x16x32_bf16 v[100:103], v[144:147], v[208:211], v[100:103]
	v_mfma_f32_16x16x32_bf16 v[96:99], v[172:175], v[208:211], v[96:99]
	v_mfma_f32_16x16x32_bf16 v[84:87], v[144:147], v[216:219], v[84:87]
	v_mfma_f32_16x16x32_bf16 v[80:83], v[172:175], v[216:219], v[80:83]
	v_mfma_f32_16x16x32_bf16 v[132:135], v[148:151], v[196:199], v[132:135]
	v_mfma_f32_16x16x32_bf16 v[128:131], v[176:179], v[196:199], v[128:131]
	v_mfma_f32_16x16x32_bf16 v[116:119], v[148:151], v[204:207], v[116:119]
	v_mfma_f32_16x16x32_bf16 v[112:115], v[176:179], v[204:207], v[112:115]
	v_mfma_f32_16x16x32_bf16 v[100:103], v[148:151], v[212:215], v[100:103]
	v_mfma_f32_16x16x32_bf16 v[96:99], v[176:179], v[212:215], v[96:99]
	v_mfma_f32_16x16x32_bf16 v[84:87], v[148:151], v[220:223], v[84:87]
	v_mfma_f32_16x16x32_bf16 v[80:83], v[176:179], v[220:223], v[80:83]
	s_setprio 0
	s_barrier
	s_add_i32 s66, s66, s31
	v_lshl_add_u64 v[224:225], s[42:43], 0, v[152:153]
	s_mov_b32 m0, s66
	ds_read_b128 v[180:183], v194 offset:16384
	ds_read_b128 v[196:199], v194 offset:17408
	ds_read_b128 v[200:203], v194 offset:18432
	ds_read_b128 v[204:207], v194 offset:19456
	ds_read_b128 v[208:211], v194 offset:20480
	ds_read_b128 v[212:215], v194 offset:21504
	ds_read_b128 v[216:219], v194 offset:22528
	ds_read_b128 v[220:223], v194 offset:23552
	global_load_lds_dwordx4 v[224:225], off
	s_add_i32 m0, s66, 0x2000
	s_add_u32 s90, s42, 0x40000
	v_lshl_add_u64 v[226:227], s[42:43], 0, v[166:167]
	s_addc_u32 s91, s43, 0
	s_add_i32 s66, s83, s31
	global_load_lds_dwordx4 v[226:227], off
	v_lshl_add_u64 v[228:229], s[90:91], 0, v[152:153]
	s_mov_b32 m0, s66
	v_lshl_add_u64 v[230:231], vcc, 0, v[164:165]
	global_load_lds_dwordx4 v[228:229], off
	v_lshl_add_u64 v[228:229], s[90:91], 0, v[166:167]
	s_add_i32 m0, s66, 0x2000
	s_nop 0
	global_load_lds_dwordx4 v[228:229], off
	v_lshl_add_u64 v[228:229], vcc, 0, v[162:163]
	s_mov_b32 m0, s33
	s_nop 0
	global_load_lds_dwordx4 v[228:229], off
	s_mov_b32 m0, s36
	s_nop 0
	global_load_lds_dwordx4 v[230:231], off
	s_waitcnt vmcnt(8)
	s_waitcnt lgkmcnt(0)
	s_barrier
	s_setprio 1
	v_mfma_f32_16x16x32_bf16 v[60:63], v[64:67], v[180:183], v[60:63]
	v_mfma_f32_16x16x32_bf16 v[56:59], v[72:75], v[180:183], v[56:59]
	v_mfma_f32_16x16x32_bf16 v[44:47], v[64:67], v[200:203], v[44:47]
	v_mfma_f32_16x16x32_bf16 v[40:43], v[72:75], v[200:203], v[40:43]
	v_mfma_f32_16x16x32_bf16 v[28:31], v[64:67], v[208:211], v[28:31]
	v_mfma_f32_16x16x32_bf16 v[24:27], v[72:75], v[208:211], v[24:27]
	v_mfma_f32_16x16x32_bf16 v[12:15], v[64:67], v[216:219], v[12:15]
	v_mfma_f32_16x16x32_bf16 v[8:11], v[72:75], v[216:219], v[8:11]
	v_mfma_f32_16x16x32_bf16 v[60:63], v[68:71], v[196:199], v[60:63]
	v_mfma_f32_16x16x32_bf16 v[56:59], v[76:79], v[196:199], v[56:59]
	v_mfma_f32_16x16x32_bf16 v[44:47], v[68:71], v[204:207], v[44:47]
	v_mfma_f32_16x16x32_bf16 v[40:43], v[76:79], v[204:207], v[40:43]
	v_mfma_f32_16x16x32_bf16 v[28:31], v[68:71], v[212:215], v[28:31]
	v_mfma_f32_16x16x32_bf16 v[24:27], v[76:79], v[212:215], v[24:27]
	v_mfma_f32_16x16x32_bf16 v[12:15], v[68:71], v[220:223], v[12:15]
	v_mfma_f32_16x16x32_bf16 v[8:11], v[76:79], v[220:223], v[8:11]
	v_mfma_f32_16x16x32_bf16 v[52:55], v[144:147], v[180:183], v[52:55]
	v_mfma_f32_16x16x32_bf16 v[48:51], v[172:175], v[180:183], v[48:51]
	v_mfma_f32_16x16x32_bf16 v[36:39], v[144:147], v[200:203], v[36:39]
	v_mfma_f32_16x16x32_bf16 v[32:35], v[172:175], v[200:203], v[32:35]
	v_mfma_f32_16x16x32_bf16 v[20:23], v[144:147], v[208:211], v[20:23]
	v_mfma_f32_16x16x32_bf16 v[16:19], v[172:175], v[208:211], v[16:19]
	v_mfma_f32_16x16x32_bf16 v[4:7], v[144:147], v[216:219], v[4:7]
	v_mfma_f32_16x16x32_bf16 v[0:3], v[172:175], v[216:219], v[0:3]
	v_mfma_f32_16x16x32_bf16 v[52:55], v[148:151], v[196:199], v[52:55]
	v_mfma_f32_16x16x32_bf16 v[48:51], v[176:179], v[196:199], v[48:51]
	v_mfma_f32_16x16x32_bf16 v[36:39], v[148:151], v[204:207], v[36:39]
	v_mfma_f32_16x16x32_bf16 v[32:35], v[176:179], v[204:207], v[32:35]
	v_mfma_f32_16x16x32_bf16 v[20:23], v[148:151], v[212:215], v[20:23]
	v_mfma_f32_16x16x32_bf16 v[16:19], v[176:179], v[212:215], v[16:19]
	v_mfma_f32_16x16x32_bf16 v[4:7], v[148:151], v[220:223], v[4:7]
	v_mfma_f32_16x16x32_bf16 v[0:3], v[176:179], v[220:223], v[0:3]
	s_setprio 0
	s_barrier
	s_add_i32 s66, 0, 0x18000
	s_add_i32 s83, 0, 0x1c000
	v_add_u32_e32 v76, s66, v185
	v_add_u32_e32 v154, s83, v185
	ds_read_b128 v[64:67], v76
	ds_read_b128 v[68:71], v76 offset:1024
	ds_read_b128 v[72:75], v76 offset:2048
	ds_read_b128 v[76:79], v76 offset:3072
	ds_read_b128 v[144:147], v154
	ds_read_b128 v[148:151], v154 offset:1024
	ds_read_b128 v[172:175], v154 offset:2048
	ds_read_b128 v[176:179], v154 offset:3072
	s_add_u32 s90, vcc_lo, 0x40000
	s_addc_u32 s91, vcc_hi, 0
	s_mov_b32 m0, s37
	v_lshl_add_u64 v[232:233], s[90:91], 0, v[162:163]
	ds_read_b128 v[180:183], v194 offset:32768
	ds_read_b128 v[196:199], v194 offset:33792
	ds_read_b128 v[200:203], v194 offset:34816
	ds_read_b128 v[204:207], v194 offset:35840
	ds_read_b128 v[208:211], v194 offset:36864
	ds_read_b128 v[212:215], v194 offset:37888
	ds_read_b128 v[216:219], v194 offset:38912
	ds_read_b128 v[220:223], v194 offset:39936
	global_load_lds_dwordx4 v[232:233], off
	v_lshl_add_u64 v[232:233], s[90:91], 0, v[164:165]
	s_mov_b32 m0, s60
	s_nop 0
	global_load_lds_dwordx4 v[232:233], off
	s_waitcnt vmcnt(8)
	s_waitcnt lgkmcnt(0)
	s_barrier
	s_setprio 1
	v_mfma_f32_16x16x32_bf16 v[140:143], v[64:67], v[180:183], v[140:143]
	v_mfma_f32_16x16x32_bf16 v[136:139], v[72:75], v[180:183], v[136:139]
	v_mfma_f32_16x16x32_bf16 v[124:127], v[64:67], v[200:203], v[124:127]
	v_mfma_f32_16x16x32_bf16 v[120:123], v[72:75], v[200:203], v[120:123]
	v_mfma_f32_16x16x32_bf16 v[108:111], v[64:67], v[208:211], v[108:111]
	v_mfma_f32_16x16x32_bf16 v[104:107], v[72:75], v[208:211], v[104:107]
	v_mfma_f32_16x16x32_bf16 v[92:95], v[64:67], v[216:219], v[92:95]
	v_mfma_f32_16x16x32_bf16 v[88:91], v[72:75], v[216:219], v[88:91]
	v_mfma_f32_16x16x32_bf16 v[140:143], v[68:71], v[196:199], v[140:143]
	v_mfma_f32_16x16x32_bf16 v[136:139], v[76:79], v[196:199], v[136:139]
	v_mfma_f32_16x16x32_bf16 v[124:127], v[68:71], v[204:207], v[124:127]
	v_mfma_f32_16x16x32_bf16 v[120:123], v[76:79], v[204:207], v[120:123]
	v_mfma_f32_16x16x32_bf16 v[108:111], v[68:71], v[212:215], v[108:111]
	v_mfma_f32_16x16x32_bf16 v[104:107], v[76:79], v[212:215], v[104:107]
	v_mfma_f32_16x16x32_bf16 v[92:95], v[68:71], v[220:223], v[92:95]
	v_mfma_f32_16x16x32_bf16 v[88:91], v[76:79], v[220:223], v[88:91]
	v_mfma_f32_16x16x32_bf16 v[132:135], v[144:147], v[180:183], v[132:135]
	v_mfma_f32_16x16x32_bf16 v[128:131], v[172:175], v[180:183], v[128:131]
	v_mfma_f32_16x16x32_bf16 v[116:119], v[144:147], v[200:203], v[116:119]
	v_mfma_f32_16x16x32_bf16 v[112:115], v[172:175], v[200:203], v[112:115]
	v_mfma_f32_16x16x32_bf16 v[100:103], v[144:147], v[208:211], v[100:103]
	v_mfma_f32_16x16x32_bf16 v[96:99], v[172:175], v[208:211], v[96:99]
	v_mfma_f32_16x16x32_bf16 v[84:87], v[144:147], v[216:219], v[84:87]
	v_mfma_f32_16x16x32_bf16 v[80:83], v[172:175], v[216:219], v[80:83]
	v_mfma_f32_16x16x32_bf16 v[132:135], v[148:151], v[196:199], v[132:135]
	v_mfma_f32_16x16x32_bf16 v[128:131], v[176:179], v[196:199], v[128:131]
	v_mfma_f32_16x16x32_bf16 v[116:119], v[148:151], v[204:207], v[116:119]
	v_mfma_f32_16x16x32_bf16 v[112:115], v[176:179], v[204:207], v[112:115]
	v_mfma_f32_16x16x32_bf16 v[100:103], v[148:151], v[212:215], v[100:103]
	v_mfma_f32_16x16x32_bf16 v[96:99], v[176:179], v[212:215], v[96:99]
	v_mfma_f32_16x16x32_bf16 v[84:87], v[148:151], v[220:223], v[84:87]
	v_mfma_f32_16x16x32_bf16 v[80:83], v[176:179], v[220:223], v[80:83]
	s_setprio 0
	s_barrier
	s_add_i32 s66, s66, s31
	v_lshl_add_u64 v[224:225], v[224:225], 0, s[70:71]
	s_mov_b32 m0, s66
	ds_read_b128 v[180:183], v194 offset:49152
	ds_read_b128 v[196:199], v194 offset:50176
	ds_read_b128 v[200:203], v194 offset:51200
	ds_read_b128 v[204:207], v194 offset:52224
	ds_read_b128 v[208:211], v194 offset:53248
	ds_read_b128 v[212:215], v194 offset:54272
	ds_read_b128 v[216:219], v194 offset:55296
	ds_read_b128 v[220:223], v194 offset:56320
	global_load_lds_dwordx4 v[224:225], off
	s_add_i32 m0, s66, 0x2000
	s_add_u32 s42, s42, 0x40080
	v_lshl_add_u64 v[224:225], v[226:227], 0, s[70:71]
	s_addc_u32 s43, s43, 0
	s_add_i32 s66, s83, s31
	global_load_lds_dwordx4 v[224:225], off
	v_lshl_add_u64 v[224:225], s[42:43], 0, v[152:153]
	s_mov_b32 m0, s66
	s_nop 0
	global_load_lds_dwordx4 v[224:225], off
	v_lshl_add_u64 v[224:225], s[42:43], 0, v[166:167]
	s_add_i32 m0, s66, 0x2000
	s_nop 0
	global_load_lds_dwordx4 v[224:225], off
	v_lshl_add_u64 v[224:225], v[228:229], 0, s[70:71]
	s_mov_b32 m0, s75
	s_nop 0
	global_load_lds_dwordx4 v[224:225], off
	v_lshl_add_u64 v[224:225], v[230:231], 0, s[70:71]
	s_mov_b32 m0, s76
	s_nop 0
	global_load_lds_dwordx4 v[224:225], off
	s_waitcnt vmcnt(8)
	s_waitcnt lgkmcnt(0)
	s_barrier
	s_setprio 1
	v_mfma_f32_16x16x32_bf16 v[60:63], v[64:67], v[180:183], v[60:63]
	v_mfma_f32_16x16x32_bf16 v[56:59], v[72:75], v[180:183], v[56:59]
	v_mfma_f32_16x16x32_bf16 v[44:47], v[64:67], v[200:203], v[44:47]
	v_mfma_f32_16x16x32_bf16 v[40:43], v[72:75], v[200:203], v[40:43]
	v_mfma_f32_16x16x32_bf16 v[28:31], v[64:67], v[208:211], v[28:31]
	v_mfma_f32_16x16x32_bf16 v[24:27], v[72:75], v[208:211], v[24:27]
	v_mfma_f32_16x16x32_bf16 v[12:15], v[64:67], v[216:219], v[12:15]
	v_mfma_f32_16x16x32_bf16 v[8:11], v[72:75], v[216:219], v[8:11]
	v_mfma_f32_16x16x32_bf16 v[60:63], v[68:71], v[196:199], v[60:63]
	v_mfma_f32_16x16x32_bf16 v[56:59], v[76:79], v[196:199], v[56:59]
	v_mfma_f32_16x16x32_bf16 v[44:47], v[68:71], v[204:207], v[44:47]
	v_mfma_f32_16x16x32_bf16 v[40:43], v[76:79], v[204:207], v[40:43]
	v_mfma_f32_16x16x32_bf16 v[28:31], v[68:71], v[212:215], v[28:31]
	v_mfma_f32_16x16x32_bf16 v[24:27], v[76:79], v[212:215], v[24:27]
	v_mfma_f32_16x16x32_bf16 v[12:15], v[68:71], v[220:223], v[12:15]
	v_mfma_f32_16x16x32_bf16 v[8:11], v[76:79], v[220:223], v[8:11]
	v_mfma_f32_16x16x32_bf16 v[52:55], v[144:147], v[180:183], v[52:55]
	v_mfma_f32_16x16x32_bf16 v[48:51], v[172:175], v[180:183], v[48:51]
	v_mfma_f32_16x16x32_bf16 v[36:39], v[144:147], v[200:203], v[36:39]
	v_mfma_f32_16x16x32_bf16 v[32:35], v[172:175], v[200:203], v[32:35]
	v_mfma_f32_16x16x32_bf16 v[20:23], v[144:147], v[208:211], v[20:23]
	v_mfma_f32_16x16x32_bf16 v[16:19], v[172:175], v[208:211], v[16:19]
	v_mfma_f32_16x16x32_bf16 v[4:7], v[144:147], v[216:219], v[4:7]
	v_mfma_f32_16x16x32_bf16 v[0:3], v[172:175], v[216:219], v[0:3]
	v_mfma_f32_16x16x32_bf16 v[52:55], v[148:151], v[196:199], v[52:55]
	v_mfma_f32_16x16x32_bf16 v[48:51], v[176:179], v[196:199], v[48:51]
	v_mfma_f32_16x16x32_bf16 v[36:39], v[148:151], v[204:207], v[36:39]
	v_mfma_f32_16x16x32_bf16 v[32:35], v[176:179], v[204:207], v[32:35]
	v_mfma_f32_16x16x32_bf16 v[20:23], v[148:151], v[212:215], v[20:23]
	v_mfma_f32_16x16x32_bf16 v[16:19], v[176:179], v[212:215], v[16:19]
	v_mfma_f32_16x16x32_bf16 v[4:7], v[148:151], v[220:223], v[4:7]
	v_mfma_f32_16x16x32_bf16 v[0:3], v[176:179], v[220:223], v[0:3]
	s_setprio 0
	s_add_i32 s65, s65, 2
	s_add_u32 s24, s24, 0x100
	s_addc_u32 s25, s25, 0
	s_add_u32 s29, s29, 0x100
	s_addc_u32 s45, s45, 0
	s_cmp_gt_u32 s65, 13
	s_barrier
	s_cbranch_scc0 .LBB0_397
	s_and_b64 vcc, exec, s[14:15]
	s_cbranch_vccz .LBB0_400
	s_barrier

.LBB0_559:
	s_add_u32 s63, s44, 0xfffc0080
	s_addc_u32 s64, s45, -1
	s_add_i32 s66, 0, 0x10000
	s_cmp_eq_u32 s62, 12
	s_cselect_b32 vcc_hi, s19, s64
	s_cselect_b32 vcc_lo, s23, s63
	s_cselect_b32 s65, s15, s61
	s_cselect_b32 s64, s43, s60
	s_add_i32 s63, 0, 0x14000
	v_add_u32_e32 v124, s66, v169
	v_add_u32_e32 v154, s63, v169
	ds_read_b128 v[112:115], v124
	ds_read_b128 v[116:119], v124 offset:1024
	ds_read_b128 v[120:123], v124 offset:2048
	ds_read_b128 v[124:127], v124 offset:3072
	ds_read_b128 v[164:167], v154
	ds_read_b128 v[172:175], v154 offset:1024
	ds_read_b128 v[176:179], v154 offset:2048
	ds_read_b128 v[180:183], v154 offset:3072
	v_lshl_add_u64 v[216:217], s[44:45], 0, v[150:151]
	s_add_i32 m0, s25, 0xc000
	ds_read_b128 v[184:187], v171
	ds_read_b128 v[188:191], v171 offset:1024
	ds_read_b128 v[192:195], v171 offset:2048
	ds_read_b128 v[196:199], v171 offset:3072
	ds_read_b128 v[200:203], v171 offset:4096
	ds_read_b128 v[204:207], v171 offset:5120
	ds_read_b128 v[208:211], v171 offset:6144
	ds_read_b128 v[212:215], v171 offset:7168
	global_load_lds_dwordx4 v[216:217], off
	v_lshl_add_u64 v[216:217], s[44:45], 0, v[162:163]
	s_add_i32 m0, s25, 0xe000
	s_nop 0
	global_load_lds_dwordx4 v[216:217], off
	s_waitcnt vmcnt(8)
	s_waitcnt lgkmcnt(0)
	s_barrier
	s_setprio 1
	v_mfma_f32_16x16x32_bf16 v[140:143], v[112:115], v[184:187], v[140:143]
	v_mfma_f32_16x16x32_bf16 v[136:139], v[120:123], v[184:187], v[136:139]
	v_mfma_f32_16x16x32_bf16 v[108:111], v[112:115], v[192:195], v[108:111]
	v_mfma_f32_16x16x32_bf16 v[104:107], v[120:123], v[192:195], v[104:107]
	v_mfma_f32_16x16x32_bf16 v[92:95], v[112:115], v[200:203], v[92:95]
	v_mfma_f32_16x16x32_bf16 v[88:91], v[120:123], v[200:203], v[88:91]
	v_mfma_f32_16x16x32_bf16 v[76:79], v[112:115], v[208:211], v[76:79]
	v_mfma_f32_16x16x32_bf16 v[72:75], v[120:123], v[208:211], v[72:75]
	v_mfma_f32_16x16x32_bf16 v[140:143], v[116:119], v[188:191], v[140:143]
	v_mfma_f32_16x16x32_bf16 v[136:139], v[124:127], v[188:191], v[136:139]
	v_mfma_f32_16x16x32_bf16 v[108:111], v[116:119], v[196:199], v[108:111]
	v_mfma_f32_16x16x32_bf16 v[104:107], v[124:127], v[196:199], v[104:107]
	v_mfma_f32_16x16x32_bf16 v[92:95], v[116:119], v[204:207], v[92:95]
	v_mfma_f32_16x16x32_bf16 v[88:91], v[124:127], v[204:207], v[88:91]
	v_mfma_f32_16x16x32_bf16 v[76:79], v[116:119], v[212:215], v[76:79]
	v_mfma_f32_16x16x32_bf16 v[72:75], v[124:127], v[212:215], v[72:75]
	v_mfma_f32_16x16x32_bf16 v[132:135], v[164:167], v[184:187], v[132:135]
	v_mfma_f32_16x16x32_bf16 v[128:131], v[176:179], v[184:187], v[128:131]
	v_mfma_f32_16x16x32_bf16 v[100:103], v[164:167], v[192:195], v[100:103]
	v_mfma_f32_16x16x32_bf16 v[96:99], v[176:179], v[192:195], v[96:99]
	v_mfma_f32_16x16x32_bf16 v[84:87], v[164:167], v[200:203], v[84:87]
	v_mfma_f32_16x16x32_bf16 v[80:83], v[176:179], v[200:203], v[80:83]
	v_mfma_f32_16x16x32_bf16 v[68:71], v[164:167], v[208:211], v[68:71]
	v_mfma_f32_16x16x32_bf16 v[64:67], v[176:179], v[208:211], v[64:67]
	v_mfma_f32_16x16x32_bf16 v[132:135], v[172:175], v[188:191], v[132:135]
	v_mfma_f32_16x16x32_bf16 v[128:131], v[180:183], v[188:191], v[128:131]
	v_mfma_f32_16x16x32_bf16 v[100:103], v[172:175], v[196:199], v[100:103]
	v_mfma_f32_16x16x32_bf16 v[96:99], v[180:183], v[196:199], v[96:99]
	v_mfma_f32_16x16x32_bf16 v[84:87], v[172:175], v[204:207], v[84:87]
	v_mfma_f32_16x16x32_bf16 v[80:83], v[180:183], v[204:207], v[80:83]
	v_mfma_f32_16x16x32_bf16 v[68:71], v[172:175], v[212:215], v[68:71]
	v_mfma_f32_16x16x32_bf16 v[64:67], v[180:183], v[212:215], v[64:67]
	s_setprio 0
	s_barrier
	s_add_i32 s66, s66, s27
	v_lshl_add_u64 v[216:217], s[64:65], 0, v[152:153]
	s_mov_b32 m0, s66
	ds_read_b128 v[184:187], v171 offset:16384
	ds_read_b128 v[188:191], v171 offset:17408
	ds_read_b128 v[192:195], v171 offset:18432
	ds_read_b128 v[196:199], v171 offset:19456
	ds_read_b128 v[200:203], v171 offset:20480
	ds_read_b128 v[204:207], v171 offset:21504
	ds_read_b128 v[208:211], v171 offset:22528
	ds_read_b128 v[212:215], v171 offset:23552
	global_load_lds_dwordx4 v[216:217], off
	s_add_i32 m0, s66, 0x2000
	s_add_u32 s68, s64, 0x40000
	v_lshl_add_u64 v[218:219], s[64:65], 0, v[148:149]
	s_addc_u32 s69, s65, 0
	s_add_i32 s63, s63, s27
	global_load_lds_dwordx4 v[218:219], off
	v_lshl_add_u64 v[220:221], s[68:69], 0, v[152:153]
	s_mov_b32 m0, s63
	v_lshl_add_u64 v[222:223], vcc, 0, v[146:147]
	global_load_lds_dwordx4 v[220:221], off
	v_lshl_add_u64 v[220:221], s[68:69], 0, v[148:149]
	s_add_i32 m0, s63, 0x2000
	s_nop 0
	global_load_lds_dwordx4 v[220:221], off
	v_lshl_add_u64 v[220:221], vcc, 0, v[144:145]
	s_mov_b32 m0, s25
	s_nop 0
	global_load_lds_dwordx4 v[220:221], off
	s_mov_b32 m0, s28
	s_nop 0
	global_load_lds_dwordx4 v[222:223], off
	s_waitcnt vmcnt(8)
	s_waitcnt lgkmcnt(0)
	s_barrier
	s_setprio 1
	v_mfma_f32_16x16x32_bf16 v[60:63], v[112:115], v[184:187], v[60:63]
	v_mfma_f32_16x16x32_bf16 v[56:59], v[120:123], v[184:187], v[56:59]
	v_mfma_f32_16x16x32_bf16 v[44:47], v[112:115], v[192:195], v[44:47]
	v_mfma_f32_16x16x32_bf16 v[40:43], v[120:123], v[192:195], v[40:43]
	v_mfma_f32_16x16x32_bf16 v[28:31], v[112:115], v[200:203], v[28:31]
	v_mfma_f32_16x16x32_bf16 v[24:27], v[120:123], v[200:203], v[24:27]
	v_mfma_f32_16x16x32_bf16 v[12:15], v[112:115], v[208:211], v[12:15]
	v_mfma_f32_16x16x32_bf16 v[8:11], v[120:123], v[208:211], v[8:11]
	v_mfma_f32_16x16x32_bf16 v[60:63], v[116:119], v[188:191], v[60:63]
	v_mfma_f32_16x16x32_bf16 v[56:59], v[124:127], v[188:191], v[56:59]
	v_mfma_f32_16x16x32_bf16 v[44:47], v[116:119], v[196:199], v[44:47]
	v_mfma_f32_16x16x32_bf16 v[40:43], v[124:127], v[196:199], v[40:43]
	v_mfma_f32_16x16x32_bf16 v[28:31], v[116:119], v[204:207], v[28:31]
	v_mfma_f32_16x16x32_bf16 v[24:27], v[124:127], v[204:207], v[24:27]
	v_mfma_f32_16x16x32_bf16 v[12:15], v[116:119], v[212:215], v[12:15]
	v_mfma_f32_16x16x32_bf16 v[8:11], v[124:127], v[212:215], v[8:11]
	v_mfma_f32_16x16x32_bf16 v[52:55], v[164:167], v[184:187], v[52:55]
	v_mfma_f32_16x16x32_bf16 v[48:51], v[176:179], v[184:187], v[48:51]
	v_mfma_f32_16x16x32_bf16 v[36:39], v[164:167], v[192:195], v[36:39]
	v_mfma_f32_16x16x32_bf16 v[32:35], v[176:179], v[192:195], v[32:35]
	v_mfma_f32_16x16x32_bf16 v[20:23], v[164:167], v[200:203], v[20:23]
	v_mfma_f32_16x16x32_bf16 v[16:19], v[176:179], v[200:203], v[16:19]
	v_mfma_f32_16x16x32_bf16 v[4:7], v[164:167], v[208:211], v[4:7]
	v_mfma_f32_16x16x32_bf16 v[0:3], v[176:179], v[208:211], v[0:3]
	v_mfma_f32_16x16x32_bf16 v[52:55], v[172:175], v[188:191], v[52:55]
	v_mfma_f32_16x16x32_bf16 v[48:51], v[180:183], v[188:191], v[48:51]
	v_mfma_f32_16x16x32_bf16 v[36:39], v[172:175], v[196:199], v[36:39]
	v_mfma_f32_16x16x32_bf16 v[32:35], v[180:183], v[196:199], v[32:35]
	v_mfma_f32_16x16x32_bf16 v[20:23], v[172:175], v[204:207], v[20:23]
	v_mfma_f32_16x16x32_bf16 v[16:19], v[180:183], v[204:207], v[16:19]
	v_mfma_f32_16x16x32_bf16 v[4:7], v[172:175], v[212:215], v[4:7]
	v_mfma_f32_16x16x32_bf16 v[0:3], v[180:183], v[212:215], v[0:3]
	s_setprio 0
	s_barrier
	s_add_i32 s63, 0, 0x18000
	s_add_i32 s66, 0, 0x1c000
	v_add_u32_e32 v124, s63, v169
	v_add_u32_e32 v154, s66, v169
	ds_read_b128 v[112:115], v124
	ds_read_b128 v[116:119], v124 offset:1024
	ds_read_b128 v[120:123], v124 offset:2048
	ds_read_b128 v[124:127], v124 offset:3072
	ds_read_b128 v[164:167], v154
	ds_read_b128 v[172:175], v154 offset:1024
	ds_read_b128 v[176:179], v154 offset:2048
	ds_read_b128 v[180:183], v154 offset:3072
	s_add_u32 s68, vcc_lo, 0x40000
	s_addc_u32 s69, vcc_hi, 0
	s_mov_b32 m0, s29
	v_lshl_add_u64 v[224:225], s[68:69], 0, v[144:145]
	ds_read_b128 v[184:187], v171 offset:32768
	ds_read_b128 v[188:191], v171 offset:33792
	ds_read_b128 v[192:195], v171 offset:34816
	ds_read_b128 v[196:199], v171 offset:35840
	ds_read_b128 v[200:203], v171 offset:36864
	ds_read_b128 v[204:207], v171 offset:37888
	ds_read_b128 v[208:211], v171 offset:38912
	ds_read_b128 v[212:215], v171 offset:39936
	global_load_lds_dwordx4 v[224:225], off
	v_lshl_add_u64 v[224:225], s[68:69], 0, v[146:147]
	s_mov_b32 m0, s30
	s_nop 0
	global_load_lds_dwordx4 v[224:225], off
	s_waitcnt vmcnt(8)
	s_waitcnt lgkmcnt(0)
	s_barrier
	s_setprio 1
	v_mfma_f32_16x16x32_bf16 v[140:143], v[112:115], v[184:187], v[140:143]
	v_mfma_f32_16x16x32_bf16 v[136:139], v[120:123], v[184:187], v[136:139]
	v_mfma_f32_16x16x32_bf16 v[108:111], v[112:115], v[192:195], v[108:111]
	v_mfma_f32_16x16x32_bf16 v[104:107], v[120:123], v[192:195], v[104:107]
	v_mfma_f32_16x16x32_bf16 v[92:95], v[112:115], v[200:203], v[92:95]
	v_mfma_f32_16x16x32_bf16 v[88:91], v[120:123], v[200:203], v[88:91]
	v_mfma_f32_16x16x32_bf16 v[76:79], v[112:115], v[208:211], v[76:79]
	v_mfma_f32_16x16x32_bf16 v[72:75], v[120:123], v[208:211], v[72:75]
	v_mfma_f32_16x16x32_bf16 v[140:143], v[116:119], v[188:191], v[140:143]
	v_mfma_f32_16x16x32_bf16 v[136:139], v[124:127], v[188:191], v[136:139]
	v_mfma_f32_16x16x32_bf16 v[108:111], v[116:119], v[196:199], v[108:111]
	v_mfma_f32_16x16x32_bf16 v[104:107], v[124:127], v[196:199], v[104:107]
	v_mfma_f32_16x16x32_bf16 v[92:95], v[116:119], v[204:207], v[92:95]
	v_mfma_f32_16x16x32_bf16 v[88:91], v[124:127], v[204:207], v[88:91]
	v_mfma_f32_16x16x32_bf16 v[76:79], v[116:119], v[212:215], v[76:79]
	v_mfma_f32_16x16x32_bf16 v[72:75], v[124:127], v[212:215], v[72:75]
	v_mfma_f32_16x16x32_bf16 v[132:135], v[164:167], v[184:187], v[132:135]
	v_mfma_f32_16x16x32_bf16 v[128:131], v[176:179], v[184:187], v[128:131]
	v_mfma_f32_16x16x32_bf16 v[100:103], v[164:167], v[192:195], v[100:103]
	v_mfma_f32_16x16x32_bf16 v[96:99], v[176:179], v[192:195], v[96:99]
	v_mfma_f32_16x16x32_bf16 v[84:87], v[164:167], v[200:203], v[84:87]
	v_mfma_f32_16x16x32_bf16 v[80:83], v[176:179], v[200:203], v[80:83]
	v_mfma_f32_16x16x32_bf16 v[68:71], v[164:167], v[208:211], v[68:71]
	v_mfma_f32_16x16x32_bf16 v[64:67], v[176:179], v[208:211], v[64:67]
	v_mfma_f32_16x16x32_bf16 v[132:135], v[172:175], v[188:191], v[132:135]
	v_mfma_f32_16x16x32_bf16 v[128:131], v[180:183], v[188:191], v[128:131]
	v_mfma_f32_16x16x32_bf16 v[100:103], v[172:175], v[196:199], v[100:103]
	v_mfma_f32_16x16x32_bf16 v[96:99], v[180:183], v[196:199], v[96:99]
	v_mfma_f32_16x16x32_bf16 v[84:87], v[172:175], v[204:207], v[84:87]
	v_mfma_f32_16x16x32_bf16 v[80:83], v[180:183], v[204:207], v[80:83]
	v_mfma_f32_16x16x32_bf16 v[68:71], v[172:175], v[212:215], v[68:71]
	v_mfma_f32_16x16x32_bf16 v[64:67], v[180:183], v[212:215], v[64:67]
	s_setprio 0
	s_barrier
	s_add_i32 s63, s63, s27
	v_lshl_add_u64 v[216:217], v[216:217], 0, s[70:71]
	s_mov_b32 m0, s63
	ds_read_b128 v[184:187], v171 offset:49152
	ds_read_b128 v[188:191], v171 offset:50176
	ds_read_b128 v[192:195], v171 offset:51200
	ds_read_b128 v[196:199], v171 offset:52224
	ds_read_b128 v[200:203], v171 offset:53248
	ds_read_b128 v[204:207], v171 offset:54272
	ds_read_b128 v[208:211], v171 offset:55296
	ds_read_b128 v[212:215], v171 offset:56320
	global_load_lds_dwordx4 v[216:217], off
	s_add_i32 m0, s63, 0x2000
	s_add_u32 s64, s64, 0x40080
	v_lshl_add_u64 v[216:217], v[218:219], 0, s[70:71]
	s_addc_u32 s65, s65, 0
	s_add_i32 s63, s66, s27
	global_load_lds_dwordx4 v[216:217], off
	v_lshl_add_u64 v[216:217], s[64:65], 0, v[152:153]
	s_mov_b32 m0, s63
	s_nop 0
	global_load_lds_dwordx4 v[216:217], off
	v_lshl_add_u64 v[216:217], s[64:65], 0, v[148:149]
	s_add_i32 m0, s63, 0x2000
	s_nop 0
	global_load_lds_dwordx4 v[216:217], off
	v_lshl_add_u64 v[216:217], v[220:221], 0, s[70:71]
	s_mov_b32 m0, s33
	s_nop 0
	global_load_lds_dwordx4 v[216:217], off
	v_lshl_add_u64 v[216:217], v[222:223], 0, s[70:71]
	s_mov_b32 m0, s36
	s_nop 0
	global_load_lds_dwordx4 v[216:217], off
	s_waitcnt vmcnt(8)
	s_waitcnt lgkmcnt(0)
	s_barrier
	s_setprio 1
	v_mfma_f32_16x16x32_bf16 v[60:63], v[112:115], v[184:187], v[60:63]
	v_mfma_f32_16x16x32_bf16 v[56:59], v[120:123], v[184:187], v[56:59]
	v_mfma_f32_16x16x32_bf16 v[44:47], v[112:115], v[192:195], v[44:47]
	v_mfma_f32_16x16x32_bf16 v[40:43], v[120:123], v[192:195], v[40:43]
	v_mfma_f32_16x16x32_bf16 v[28:31], v[112:115], v[200:203], v[28:31]
	v_mfma_f32_16x16x32_bf16 v[24:27], v[120:123], v[200:203], v[24:27]
	v_mfma_f32_16x16x32_bf16 v[12:15], v[112:115], v[208:211], v[12:15]
	v_mfma_f32_16x16x32_bf16 v[8:11], v[120:123], v[208:211], v[8:11]
	v_mfma_f32_16x16x32_bf16 v[60:63], v[116:119], v[188:191], v[60:63]
	v_mfma_f32_16x16x32_bf16 v[56:59], v[124:127], v[188:191], v[56:59]
	v_mfma_f32_16x16x32_bf16 v[44:47], v[116:119], v[196:199], v[44:47]
	v_mfma_f32_16x16x32_bf16 v[40:43], v[124:127], v[196:199], v[40:43]
	v_mfma_f32_16x16x32_bf16 v[28:31], v[116:119], v[204:207], v[28:31]
	v_mfma_f32_16x16x32_bf16 v[24:27], v[124:127], v[204:207], v[24:27]
	v_mfma_f32_16x16x32_bf16 v[12:15], v[116:119], v[212:215], v[12:15]
	v_mfma_f32_16x16x32_bf16 v[8:11], v[124:127], v[212:215], v[8:11]
	v_mfma_f32_16x16x32_bf16 v[52:55], v[164:167], v[184:187], v[52:55]
	v_mfma_f32_16x16x32_bf16 v[48:51], v[176:179], v[184:187], v[48:51]
	v_mfma_f32_16x16x32_bf16 v[36:39], v[164:167], v[192:195], v[36:39]
	v_mfma_f32_16x16x32_bf16 v[32:35], v[176:179], v[192:195], v[32:35]
	v_mfma_f32_16x16x32_bf16 v[20:23], v[164:167], v[200:203], v[20:23]
	v_mfma_f32_16x16x32_bf16 v[16:19], v[176:179], v[200:203], v[16:19]
	v_mfma_f32_16x16x32_bf16 v[4:7], v[164:167], v[208:211], v[4:7]
	v_mfma_f32_16x16x32_bf16 v[0:3], v[176:179], v[208:211], v[0:3]
	v_mfma_f32_16x16x32_bf16 v[52:55], v[172:175], v[188:191], v[52:55]
	v_mfma_f32_16x16x32_bf16 v[48:51], v[180:183], v[188:191], v[48:51]
	v_mfma_f32_16x16x32_bf16 v[36:39], v[172:175], v[196:199], v[36:39]
	v_mfma_f32_16x16x32_bf16 v[32:35], v[180:183], v[196:199], v[32:35]
	v_mfma_f32_16x16x32_bf16 v[20:23], v[172:175], v[204:207], v[20:23]
	v_mfma_f32_16x16x32_bf16 v[16:19], v[180:183], v[204:207], v[16:19]
	v_mfma_f32_16x16x32_bf16 v[4:7], v[172:175], v[212:215], v[4:7]
	v_mfma_f32_16x16x32_bf16 v[0:3], v[180:183], v[212:215], v[0:3]
	s_setprio 0
	s_add_i32 s62, s62, 2
	s_add_u32 s44, s44, 0x100
	s_addc_u32 s45, s45, 0
	s_add_u32 s60, s60, 0x100
	s_addc_u32 s61, s61, 0
	s_cmp_gt_u32 s62, 13
	s_barrier
	s_cbranch_scc0 .LBB0_559
	s_and_b64 vcc, exec, s[12:13]
	s_cbranch_vccz .LBB0_562
	s_barrier

.LBB0_635:
	s_add_u32 s12, s10, 0xfff00080
	s_addc_u32 s13, s11, -1
	s_add_i32 s27, 0, 0x10000
	s_cmp_eq_u32 s26, 60
	s_cselect_b32 s21, s19, s13
	s_cselect_b32 s20, s22, s12
	s_cselect_b32 s13, s17, s25
	s_cselect_b32 s12, s23, s24
	s_add_i32 s30, 0, 0x14000
	v_add_u32_e32 v100, s27, v249
	v_add_u32_e32 v154, s30, v249
	ds_read_b128 v[88:91], v100
	ds_read_b128 v[92:95], v100 offset:1024
	ds_read_b128 v[96:99], v100 offset:2048
	ds_read_b128 v[100:103], v100 offset:3072
	ds_read_b128 v[164:167], v154
	ds_read_b128 v[168:171], v154 offset:1024
	ds_read_b128 v[172:175], v154 offset:2048
	ds_read_b128 v[176:179], v154 offset:3072
	v_lshl_add_u64 v[212:213], s[10:11], 0, v[150:151]
	s_add_i32 m0, s60, 0xc000
	ds_read_b128 v[180:183], v251
	ds_read_b128 v[184:187], v251 offset:1024
	ds_read_b128 v[188:191], v251 offset:2048
	ds_read_b128 v[192:195], v251 offset:3072
	ds_read_b128 v[196:199], v251 offset:4096
	ds_read_b128 v[200:203], v251 offset:5120
	ds_read_b128 v[204:207], v251 offset:6144
	ds_read_b128 v[208:211], v251 offset:7168
	global_load_lds_dwordx4 v[212:213], off
	v_lshl_add_u64 v[212:213], s[10:11], 0, v[162:163]
	s_add_i32 m0, s60, 0xe000
	s_nop 0
	global_load_lds_dwordx4 v[212:213], off
	s_waitcnt vmcnt(8)
	s_waitcnt lgkmcnt(0)
	s_barrier
	s_setprio 1
	v_mfma_f32_16x16x32_bf16 v[140:143], v[88:91], v[180:183], v[140:143]
	v_mfma_f32_16x16x32_bf16 v[136:139], v[96:99], v[180:183], v[136:139]
	v_mfma_f32_16x16x32_bf16 v[132:135], v[88:91], v[188:191], v[132:135]
	v_mfma_f32_16x16x32_bf16 v[128:131], v[96:99], v[188:191], v[128:131]
	v_mfma_f32_16x16x32_bf16 v[124:127], v[88:91], v[196:199], v[124:127]
	v_mfma_f32_16x16x32_bf16 v[120:123], v[96:99], v[196:199], v[120:123]
	v_mfma_f32_16x16x32_bf16 v[116:119], v[88:91], v[204:207], v[116:119]
	v_mfma_f32_16x16x32_bf16 v[112:115], v[96:99], v[204:207], v[112:115]
	v_mfma_f32_16x16x32_bf16 v[140:143], v[92:95], v[184:187], v[140:143]
	v_mfma_f32_16x16x32_bf16 v[136:139], v[100:103], v[184:187], v[136:139]
	v_mfma_f32_16x16x32_bf16 v[132:135], v[92:95], v[192:195], v[132:135]
	v_mfma_f32_16x16x32_bf16 v[128:131], v[100:103], v[192:195], v[128:131]
	v_mfma_f32_16x16x32_bf16 v[124:127], v[92:95], v[200:203], v[124:127]
	v_mfma_f32_16x16x32_bf16 v[120:123], v[100:103], v[200:203], v[120:123]
	v_mfma_f32_16x16x32_bf16 v[116:119], v[92:95], v[208:211], v[116:119]
	v_mfma_f32_16x16x32_bf16 v[112:115], v[100:103], v[208:211], v[112:115]
	v_mfma_f32_16x16x32_bf16 v[60:63], v[164:167], v[180:183], v[60:63]
	v_mfma_f32_16x16x32_bf16 v[56:59], v[172:175], v[180:183], v[56:59]
	v_mfma_f32_16x16x32_bf16 v[52:55], v[164:167], v[188:191], v[52:55]
	v_mfma_f32_16x16x32_bf16 v[48:51], v[172:175], v[188:191], v[48:51]
	v_mfma_f32_16x16x32_bf16 v[44:47], v[164:167], v[196:199], v[44:47]
	v_mfma_f32_16x16x32_bf16 v[40:43], v[172:175], v[196:199], v[40:43]
	v_mfma_f32_16x16x32_bf16 v[36:39], v[164:167], v[204:207], v[36:39]
	v_mfma_f32_16x16x32_bf16 v[32:35], v[172:175], v[204:207], v[32:35]
	v_mfma_f32_16x16x32_bf16 v[60:63], v[168:171], v[184:187], v[60:63]
	v_mfma_f32_16x16x32_bf16 v[56:59], v[176:179], v[184:187], v[56:59]
	v_mfma_f32_16x16x32_bf16 v[52:55], v[168:171], v[192:195], v[52:55]
	v_mfma_f32_16x16x32_bf16 v[48:51], v[176:179], v[192:195], v[48:51]
	v_mfma_f32_16x16x32_bf16 v[44:47], v[168:171], v[200:203], v[44:47]
	v_mfma_f32_16x16x32_bf16 v[40:43], v[176:179], v[200:203], v[40:43]
	v_mfma_f32_16x16x32_bf16 v[36:39], v[168:171], v[208:211], v[36:39]
	v_mfma_f32_16x16x32_bf16 v[32:35], v[176:179], v[208:211], v[32:35]
	s_setprio 0
	s_barrier
	s_add_i32 s27, s27, s62
	v_lshl_add_u64 v[212:213], s[12:13], 0, v[152:153]
	s_mov_b32 m0, s27
	ds_read_b128 v[180:183], v251 offset:16384
	ds_read_b128 v[184:187], v251 offset:17408
	ds_read_b128 v[188:191], v251 offset:18432
	ds_read_b128 v[192:195], v251 offset:19456
	ds_read_b128 v[196:199], v251 offset:20480
	ds_read_b128 v[200:203], v251 offset:21504
	ds_read_b128 v[204:207], v251 offset:22528
	ds_read_b128 v[208:211], v251 offset:23552
	global_load_lds_dwordx4 v[212:213], off
	s_add_i32 m0, s27, 0x2000
	s_add_u32 s28, s12, 0x100000
	v_lshl_add_u64 v[214:215], s[12:13], 0, v[148:149]
	s_addc_u32 s29, s13, 0
	s_add_i32 s27, s30, s62
	global_load_lds_dwordx4 v[214:215], off
	v_lshl_add_u64 v[216:217], s[28:29], 0, v[152:153]
	s_mov_b32 m0, s27
	v_lshl_add_u64 v[218:219], s[20:21], 0, v[146:147]
	global_load_lds_dwordx4 v[216:217], off
	v_lshl_add_u64 v[216:217], s[28:29], 0, v[148:149]
	s_add_i32 m0, s27, 0x2000
	s_nop 0
	global_load_lds_dwordx4 v[216:217], off
	v_lshl_add_u64 v[216:217], s[20:21], 0, v[144:145]
	s_mov_b32 m0, s60
	s_nop 0
	global_load_lds_dwordx4 v[216:217], off
	s_mov_b32 m0, s33
	s_nop 0
	global_load_lds_dwordx4 v[218:219], off
	s_waitcnt vmcnt(8)
	s_waitcnt lgkmcnt(0)
	s_barrier
	s_setprio 1
	v_mfma_f32_16x16x32_bf16 v[108:111], v[88:91], v[180:183], v[108:111]
	v_mfma_f32_16x16x32_bf16 v[104:107], v[96:99], v[180:183], v[104:107]
	v_mfma_f32_16x16x32_bf16 v[84:87], v[88:91], v[188:191], v[84:87]
	v_mfma_f32_16x16x32_bf16 v[80:83], v[96:99], v[188:191], v[80:83]
	v_mfma_f32_16x16x32_bf16 v[76:79], v[88:91], v[196:199], v[76:79]
	v_mfma_f32_16x16x32_bf16 v[72:75], v[96:99], v[196:199], v[72:75]
	v_mfma_f32_16x16x32_bf16 v[68:71], v[88:91], v[204:207], v[68:71]
	v_mfma_f32_16x16x32_bf16 v[64:67], v[96:99], v[204:207], v[64:67]
	v_mfma_f32_16x16x32_bf16 v[108:111], v[92:95], v[184:187], v[108:111]
	v_mfma_f32_16x16x32_bf16 v[104:107], v[100:103], v[184:187], v[104:107]
	v_mfma_f32_16x16x32_bf16 v[84:87], v[92:95], v[192:195], v[84:87]
	v_mfma_f32_16x16x32_bf16 v[80:83], v[100:103], v[192:195], v[80:83]
	v_mfma_f32_16x16x32_bf16 v[76:79], v[92:95], v[200:203], v[76:79]
	v_mfma_f32_16x16x32_bf16 v[72:75], v[100:103], v[200:203], v[72:75]
	v_mfma_f32_16x16x32_bf16 v[68:71], v[92:95], v[208:211], v[68:71]
	v_mfma_f32_16x16x32_bf16 v[64:67], v[100:103], v[208:211], v[64:67]
	v_mfma_f32_16x16x32_bf16 v[28:31], v[164:167], v[180:183], v[28:31]
	v_mfma_f32_16x16x32_bf16 v[24:27], v[172:175], v[180:183], v[24:27]
	v_mfma_f32_16x16x32_bf16 v[20:23], v[164:167], v[188:191], v[20:23]
	v_mfma_f32_16x16x32_bf16 v[16:19], v[172:175], v[188:191], v[16:19]
	v_mfma_f32_16x16x32_bf16 v[12:15], v[164:167], v[196:199], v[12:15]
	v_mfma_f32_16x16x32_bf16 v[8:11], v[172:175], v[196:199], v[8:11]
	v_mfma_f32_16x16x32_bf16 v[4:7], v[164:167], v[204:207], v[4:7]
	v_mfma_f32_16x16x32_bf16 v[0:3], v[172:175], v[204:207], v[0:3]
	v_mfma_f32_16x16x32_bf16 v[28:31], v[168:171], v[184:187], v[28:31]
	v_mfma_f32_16x16x32_bf16 v[24:27], v[176:179], v[184:187], v[24:27]
	v_mfma_f32_16x16x32_bf16 v[20:23], v[168:171], v[192:195], v[20:23]
	v_mfma_f32_16x16x32_bf16 v[16:19], v[176:179], v[192:195], v[16:19]
	v_mfma_f32_16x16x32_bf16 v[12:15], v[168:171], v[200:203], v[12:15]
	v_mfma_f32_16x16x32_bf16 v[8:11], v[176:179], v[200:203], v[8:11]
	v_mfma_f32_16x16x32_bf16 v[4:7], v[168:171], v[208:211], v[4:7]
	v_mfma_f32_16x16x32_bf16 v[0:3], v[176:179], v[208:211], v[0:3]
	s_setprio 0
	s_barrier
	s_add_i32 s27, 0, 0x18000
	s_add_i32 s28, 0, 0x1c000
	v_add_u32_e32 v100, s27, v249
	v_add_u32_e32 v154, s28, v249
	ds_read_b128 v[88:91], v100
	ds_read_b128 v[92:95], v100 offset:1024
	ds_read_b128 v[96:99], v100 offset:2048
	ds_read_b128 v[100:103], v100 offset:3072
	ds_read_b128 v[164:167], v154
	ds_read_b128 v[168:171], v154 offset:1024
	ds_read_b128 v[172:175], v154 offset:2048
	ds_read_b128 v[176:179], v154 offset:3072
	s_add_u32 s20, s20, 0x100000
	s_addc_u32 s21, s21, 0
	s_mov_b32 m0, s74
	v_lshl_add_u64 v[220:221], s[20:21], 0, v[144:145]
	ds_read_b128 v[180:183], v251 offset:32768
	ds_read_b128 v[184:187], v251 offset:33792
	ds_read_b128 v[188:191], v251 offset:34816
	ds_read_b128 v[192:195], v251 offset:35840
	ds_read_b128 v[196:199], v251 offset:36864
	ds_read_b128 v[200:203], v251 offset:37888
	ds_read_b128 v[204:207], v251 offset:38912
	ds_read_b128 v[208:211], v251 offset:39936
	global_load_lds_dwordx4 v[220:221], off
	v_lshl_add_u64 v[220:221], s[20:21], 0, v[146:147]
	s_mov_b32 m0, s75
	s_nop 0
	global_load_lds_dwordx4 v[220:221], off
	s_waitcnt vmcnt(8)
	s_waitcnt lgkmcnt(0)
	s_barrier
	s_setprio 1
	v_mfma_f32_16x16x32_bf16 v[140:143], v[88:91], v[180:183], v[140:143]
	v_mfma_f32_16x16x32_bf16 v[136:139], v[96:99], v[180:183], v[136:139]
	v_mfma_f32_16x16x32_bf16 v[132:135], v[88:91], v[188:191], v[132:135]
	v_mfma_f32_16x16x32_bf16 v[128:131], v[96:99], v[188:191], v[128:131]
	v_mfma_f32_16x16x32_bf16 v[124:127], v[88:91], v[196:199], v[124:127]
	v_mfma_f32_16x16x32_bf16 v[120:123], v[96:99], v[196:199], v[120:123]
	v_mfma_f32_16x16x32_bf16 v[116:119], v[88:91], v[204:207], v[116:119]
	v_mfma_f32_16x16x32_bf16 v[112:115], v[96:99], v[204:207], v[112:115]
	v_mfma_f32_16x16x32_bf16 v[140:143], v[92:95], v[184:187], v[140:143]
	v_mfma_f32_16x16x32_bf16 v[136:139], v[100:103], v[184:187], v[136:139]
	v_mfma_f32_16x16x32_bf16 v[132:135], v[92:95], v[192:195], v[132:135]
	v_mfma_f32_16x16x32_bf16 v[128:131], v[100:103], v[192:195], v[128:131]
	v_mfma_f32_16x16x32_bf16 v[124:127], v[92:95], v[200:203], v[124:127]
	v_mfma_f32_16x16x32_bf16 v[120:123], v[100:103], v[200:203], v[120:123]
	v_mfma_f32_16x16x32_bf16 v[116:119], v[92:95], v[208:211], v[116:119]
	v_mfma_f32_16x16x32_bf16 v[112:115], v[100:103], v[208:211], v[112:115]
	v_mfma_f32_16x16x32_bf16 v[60:63], v[164:167], v[180:183], v[60:63]
	v_mfma_f32_16x16x32_bf16 v[56:59], v[172:175], v[180:183], v[56:59]
	v_mfma_f32_16x16x32_bf16 v[52:55], v[164:167], v[188:191], v[52:55]
	v_mfma_f32_16x16x32_bf16 v[48:51], v[172:175], v[188:191], v[48:51]
	v_mfma_f32_16x16x32_bf16 v[44:47], v[164:167], v[196:199], v[44:47]
	v_mfma_f32_16x16x32_bf16 v[40:43], v[172:175], v[196:199], v[40:43]
	v_mfma_f32_16x16x32_bf16 v[36:39], v[164:167], v[204:207], v[36:39]
	v_mfma_f32_16x16x32_bf16 v[32:35], v[172:175], v[204:207], v[32:35]
	v_mfma_f32_16x16x32_bf16 v[60:63], v[168:171], v[184:187], v[60:63]
	v_mfma_f32_16x16x32_bf16 v[56:59], v[176:179], v[184:187], v[56:59]
	v_mfma_f32_16x16x32_bf16 v[52:55], v[168:171], v[192:195], v[52:55]
	v_mfma_f32_16x16x32_bf16 v[48:51], v[176:179], v[192:195], v[48:51]
	v_mfma_f32_16x16x32_bf16 v[44:47], v[168:171], v[200:203], v[44:47]
	v_mfma_f32_16x16x32_bf16 v[40:43], v[176:179], v[200:203], v[40:43]
	v_mfma_f32_16x16x32_bf16 v[36:39], v[168:171], v[208:211], v[36:39]
	v_mfma_f32_16x16x32_bf16 v[32:35], v[176:179], v[208:211], v[32:35]
	s_setprio 0
	s_barrier
	s_add_i32 s20, s27, s62
	v_lshl_add_u64 v[212:213], v[212:213], 0, s[70:71]
	s_mov_b32 m0, s20
	ds_read_b128 v[180:183], v251 offset:49152
	ds_read_b128 v[184:187], v251 offset:50176
	ds_read_b128 v[188:191], v251 offset:51200
	ds_read_b128 v[192:195], v251 offset:52224
	ds_read_b128 v[196:199], v251 offset:53248
	ds_read_b128 v[200:203], v251 offset:54272
	ds_read_b128 v[204:207], v251 offset:55296
	ds_read_b128 v[208:211], v251 offset:56320
	global_load_lds_dwordx4 v[212:213], off
	s_add_i32 m0, s20, 0x2000
	s_add_u32 s12, s12, 0x100080
	v_lshl_add_u64 v[212:213], v[214:215], 0, s[70:71]
	s_addc_u32 s13, s13, 0
	s_add_i32 s20, s28, s62
	global_load_lds_dwordx4 v[212:213], off
	v_lshl_add_u64 v[212:213], s[12:13], 0, v[152:153]
	s_mov_b32 m0, s20
	s_nop 0
	global_load_lds_dwordx4 v[212:213], off
	v_lshl_add_u64 v[212:213], s[12:13], 0, v[148:149]
	s_add_i32 m0, s20, 0x2000
	s_nop 0
	global_load_lds_dwordx4 v[212:213], off
	v_lshl_add_u64 v[212:213], v[216:217], 0, s[70:71]
	s_mov_b32 m0, s69
	s_nop 0
	global_load_lds_dwordx4 v[212:213], off
	v_lshl_add_u64 v[212:213], v[218:219], 0, s[70:71]
	s_mov_b32 m0, s92
	s_nop 0
	global_load_lds_dwordx4 v[212:213], off
	s_waitcnt vmcnt(8)
	s_waitcnt lgkmcnt(0)
	s_barrier
	s_setprio 1
	v_mfma_f32_16x16x32_bf16 v[108:111], v[88:91], v[180:183], v[108:111]
	v_mfma_f32_16x16x32_bf16 v[104:107], v[96:99], v[180:183], v[104:107]
	v_mfma_f32_16x16x32_bf16 v[84:87], v[88:91], v[188:191], v[84:87]
	v_mfma_f32_16x16x32_bf16 v[80:83], v[96:99], v[188:191], v[80:83]
	v_mfma_f32_16x16x32_bf16 v[76:79], v[88:91], v[196:199], v[76:79]
	v_mfma_f32_16x16x32_bf16 v[72:75], v[96:99], v[196:199], v[72:75]
	v_mfma_f32_16x16x32_bf16 v[68:71], v[88:91], v[204:207], v[68:71]
	v_mfma_f32_16x16x32_bf16 v[64:67], v[96:99], v[204:207], v[64:67]
	v_mfma_f32_16x16x32_bf16 v[108:111], v[92:95], v[184:187], v[108:111]
	v_mfma_f32_16x16x32_bf16 v[104:107], v[100:103], v[184:187], v[104:107]
	v_mfma_f32_16x16x32_bf16 v[84:87], v[92:95], v[192:195], v[84:87]
	v_mfma_f32_16x16x32_bf16 v[80:83], v[100:103], v[192:195], v[80:83]
	v_mfma_f32_16x16x32_bf16 v[76:79], v[92:95], v[200:203], v[76:79]
	v_mfma_f32_16x16x32_bf16 v[72:75], v[100:103], v[200:203], v[72:75]
	v_mfma_f32_16x16x32_bf16 v[68:71], v[92:95], v[208:211], v[68:71]
	v_mfma_f32_16x16x32_bf16 v[64:67], v[100:103], v[208:211], v[64:67]
	v_mfma_f32_16x16x32_bf16 v[28:31], v[164:167], v[180:183], v[28:31]
	v_mfma_f32_16x16x32_bf16 v[24:27], v[172:175], v[180:183], v[24:27]
	v_mfma_f32_16x16x32_bf16 v[20:23], v[164:167], v[188:191], v[20:23]
	v_mfma_f32_16x16x32_bf16 v[16:19], v[172:175], v[188:191], v[16:19]
	v_mfma_f32_16x16x32_bf16 v[12:15], v[164:167], v[196:199], v[12:15]
	v_mfma_f32_16x16x32_bf16 v[8:11], v[172:175], v[196:199], v[8:11]
	v_mfma_f32_16x16x32_bf16 v[4:7], v[164:167], v[204:207], v[4:7]
	v_mfma_f32_16x16x32_bf16 v[0:3], v[172:175], v[204:207], v[0:3]
	v_mfma_f32_16x16x32_bf16 v[28:31], v[168:171], v[184:187], v[28:31]
	v_mfma_f32_16x16x32_bf16 v[24:27], v[176:179], v[184:187], v[24:27]
	v_mfma_f32_16x16x32_bf16 v[20:23], v[168:171], v[192:195], v[20:23]
	v_mfma_f32_16x16x32_bf16 v[16:19], v[176:179], v[192:195], v[16:19]
	v_mfma_f32_16x16x32_bf16 v[12:15], v[168:171], v[200:203], v[12:15]
	v_mfma_f32_16x16x32_bf16 v[8:11], v[176:179], v[200:203], v[8:11]
	v_mfma_f32_16x16x32_bf16 v[4:7], v[168:171], v[208:211], v[4:7]
	v_mfma_f32_16x16x32_bf16 v[0:3], v[176:179], v[208:211], v[0:3]
	s_setprio 0
	s_add_i32 s26, s26, 2
	s_add_u32 s10, s10, 0x100
	s_addc_u32 s11, s11, 0
	s_add_u32 s24, s24, 0x100
	s_addc_u32 s25, s25, 0
	s_cmp_gt_u32 s26, 61
	s_barrier
	s_cbranch_scc0 .LBB0_635
	s_and_b64 vcc, exec, s[0:1]
	s_cbranch_vccz .LBB0_638
	s_barrier

.LBB0_790:
	s_add_u32 s30, s28, 0xfffc0080
	s_addc_u32 s31, s29, -1
	s_add_i32 s82, 0, 0x10000
	s_cmp_eq_u32 s77, 12
	s_cselect_b32 s69, s63, s31
	s_cselect_b32 s68, s73, s30
	s_cselect_b32 s31, s45, s76
	s_cselect_b32 s30, s74, s75
	s_add_i32 s84, 0, 0x14000
	v_add_u32_e32 v118, s82, v167
	v_add_u32_e32 v164, s84, v167
	ds_read_b128 v[102:105], v118
	ds_read_b128 v[110:113], v118 offset:1024
	ds_read_b128 v[114:117], v118 offset:2048
	ds_read_b128 v[118:121], v118 offset:3072
	ds_read_b128 v[160:163], v164
	ds_read_b128 v[172:175], v164 offset:1024
	ds_read_b128 v[176:179], v164 offset:2048
	ds_read_b128 v[180:183], v164 offset:3072
	v_lshl_add_u64 v[164:165], s[28:29], 0, v[156:157]
	s_add_i32 m0, s11, 0xc000
	ds_read_b128 v[190:193], v171
	ds_read_b128 v[194:197], v171 offset:1024
	ds_read_b128 v[198:201], v171 offset:2048
	ds_read_b128 v[202:205], v171 offset:3072
	ds_read_b128 v[206:209], v171 offset:4096
	ds_read_b128 v[210:213], v171 offset:5120
	ds_read_b128 v[214:217], v171 offset:6144
	ds_read_b128 v[218:221], v171 offset:7168
	global_load_lds_dwordx4 v[164:165], off
	v_lshl_add_u64 v[164:165], s[28:29], 0, v[158:159]
	s_add_i32 m0, s11, 0xe000
	s_nop 0
	global_load_lds_dwordx4 v[164:165], off
	s_waitcnt vmcnt(8)
	s_waitcnt lgkmcnt(0)
	s_barrier
	s_setprio 1
	v_mfma_f32_16x16x32_bf16 v[142:145], v[102:105], v[190:193], v[142:145]
	v_mfma_f32_16x16x32_bf16 v[138:141], v[114:117], v[190:193], v[138:141]
	v_mfma_f32_16x16x32_bf16 v[126:129], v[102:105], v[198:201], v[126:129]
	v_mfma_f32_16x16x32_bf16 v[122:125], v[114:117], v[198:201], v[122:125]
	v_mfma_f32_16x16x32_bf16 v[94:97], v[102:105], v[206:209], v[94:97]
	v_mfma_f32_16x16x32_bf16 v[90:93], v[114:117], v[206:209], v[90:93]
	v_mfma_f32_16x16x32_bf16 v[78:81], v[102:105], v[214:217], v[78:81]
	v_mfma_f32_16x16x32_bf16 v[74:77], v[114:117], v[214:217], v[74:77]
	v_mfma_f32_16x16x32_bf16 v[142:145], v[110:113], v[194:197], v[142:145]
	v_mfma_f32_16x16x32_bf16 v[138:141], v[118:121], v[194:197], v[138:141]
	v_mfma_f32_16x16x32_bf16 v[126:129], v[110:113], v[202:205], v[126:129]
	v_mfma_f32_16x16x32_bf16 v[122:125], v[118:121], v[202:205], v[122:125]
	v_mfma_f32_16x16x32_bf16 v[94:97], v[110:113], v[210:213], v[94:97]
	v_mfma_f32_16x16x32_bf16 v[90:93], v[118:121], v[210:213], v[90:93]
	v_mfma_f32_16x16x32_bf16 v[78:81], v[110:113], v[218:221], v[78:81]
	v_mfma_f32_16x16x32_bf16 v[74:77], v[118:121], v[218:221], v[74:77]
	v_mfma_f32_16x16x32_bf16 v[134:137], v[160:163], v[190:193], v[134:137]
	v_mfma_f32_16x16x32_bf16 v[130:133], v[176:179], v[190:193], v[130:133]
	v_mfma_f32_16x16x32_bf16 v[106:109], v[160:163], v[198:201], v[106:109]
	v_mfma_f32_16x16x32_bf16 v[98:101], v[176:179], v[198:201], v[98:101]
	v_mfma_f32_16x16x32_bf16 v[86:89], v[160:163], v[206:209], v[86:89]
	v_mfma_f32_16x16x32_bf16 v[82:85], v[176:179], v[206:209], v[82:85]
	v_mfma_f32_16x16x32_bf16 v[70:73], v[160:163], v[214:217], v[70:73]
	v_mfma_f32_16x16x32_bf16 v[66:69], v[176:179], v[214:217], v[66:69]
	v_mfma_f32_16x16x32_bf16 v[134:137], v[172:175], v[194:197], v[134:137]
	v_mfma_f32_16x16x32_bf16 v[130:133], v[180:183], v[194:197], v[130:133]
	v_mfma_f32_16x16x32_bf16 v[106:109], v[172:175], v[202:205], v[106:109]
	v_mfma_f32_16x16x32_bf16 v[98:101], v[180:183], v[202:205], v[98:101]
	v_mfma_f32_16x16x32_bf16 v[86:89], v[172:175], v[210:213], v[86:89]
	v_mfma_f32_16x16x32_bf16 v[82:85], v[180:183], v[210:213], v[82:85]
	v_mfma_f32_16x16x32_bf16 v[70:73], v[172:175], v[218:221], v[70:73]
	v_mfma_f32_16x16x32_bf16 v[66:69], v[180:183], v[218:221], v[66:69]
	s_setprio 0
	s_barrier
	s_add_i32 s82, s82, s10
	v_lshl_add_u64 v[164:165], s[30:31], 0, v[148:149]
	s_mov_b32 m0, s82
	ds_read_b128 v[190:193], v171 offset:16384
	ds_read_b128 v[194:197], v171 offset:17408
	ds_read_b128 v[198:201], v171 offset:18432
	ds_read_b128 v[202:205], v171 offset:19456
	ds_read_b128 v[206:209], v171 offset:20480
	ds_read_b128 v[210:213], v171 offset:21504
	ds_read_b128 v[214:217], v171 offset:22528
	ds_read_b128 v[218:221], v171 offset:23552
	global_load_lds_dwordx4 v[164:165], off
	s_add_i32 m0, s82, 0x2000
	s_add_u32 s82, s30, 0x40000
	v_lshl_add_u64 v[168:169], s[30:31], 0, v[152:153]
	s_addc_u32 s83, s31, 0
	s_add_i32 s84, s84, s10
	global_load_lds_dwordx4 v[168:169], off
	v_lshl_add_u64 v[184:185], s[82:83], 0, v[148:149]
	s_mov_b32 m0, s84
	v_lshl_add_u64 v[222:223], s[68:69], 0, v[150:151]
	global_load_lds_dwordx4 v[184:185], off
	v_lshl_add_u64 v[184:185], s[82:83], 0, v[152:153]
	s_add_i32 m0, s84, 0x2000
	s_nop 0
	global_load_lds_dwordx4 v[184:185], off
	v_lshl_add_u64 v[184:185], s[68:69], 0, v[146:147]
	s_mov_b32 m0, s11
	s_nop 0
	global_load_lds_dwordx4 v[184:185], off
	s_mov_b32 m0, s13
	s_nop 0
	global_load_lds_dwordx4 v[222:223], off
	s_waitcnt vmcnt(8)
	s_waitcnt lgkmcnt(0)
	s_barrier
	s_setprio 1
	v_mfma_f32_16x16x32_bf16 v[60:63], v[102:105], v[190:193], v[60:63]
	v_mfma_f32_16x16x32_bf16 v[56:59], v[114:117], v[190:193], v[56:59]
	v_mfma_f32_16x16x32_bf16 v[44:47], v[102:105], v[198:201], v[44:47]
	v_mfma_f32_16x16x32_bf16 v[40:43], v[114:117], v[198:201], v[40:43]
	v_mfma_f32_16x16x32_bf16 v[28:31], v[102:105], v[206:209], v[28:31]
	v_mfma_f32_16x16x32_bf16 v[24:27], v[114:117], v[206:209], v[24:27]
	v_mfma_f32_16x16x32_bf16 v[12:15], v[102:105], v[214:217], v[12:15]
	v_mfma_f32_16x16x32_bf16 v[8:11], v[114:117], v[214:217], v[8:11]
	v_mfma_f32_16x16x32_bf16 v[60:63], v[110:113], v[194:197], v[60:63]
	v_mfma_f32_16x16x32_bf16 v[56:59], v[118:121], v[194:197], v[56:59]
	v_mfma_f32_16x16x32_bf16 v[44:47], v[110:113], v[202:205], v[44:47]
	v_mfma_f32_16x16x32_bf16 v[40:43], v[118:121], v[202:205], v[40:43]
	v_mfma_f32_16x16x32_bf16 v[28:31], v[110:113], v[210:213], v[28:31]
	v_mfma_f32_16x16x32_bf16 v[24:27], v[118:121], v[210:213], v[24:27]
	v_mfma_f32_16x16x32_bf16 v[12:15], v[110:113], v[218:221], v[12:15]
	v_mfma_f32_16x16x32_bf16 v[8:11], v[118:121], v[218:221], v[8:11]
	v_mfma_f32_16x16x32_bf16 v[52:55], v[160:163], v[190:193], v[52:55]
	v_mfma_f32_16x16x32_bf16 v[48:51], v[176:179], v[190:193], v[48:51]
	v_mfma_f32_16x16x32_bf16 v[36:39], v[160:163], v[198:201], v[36:39]
	v_mfma_f32_16x16x32_bf16 v[32:35], v[176:179], v[198:201], v[32:35]
	v_mfma_f32_16x16x32_bf16 v[20:23], v[160:163], v[206:209], v[20:23]
	v_mfma_f32_16x16x32_bf16 v[16:19], v[176:179], v[206:209], v[16:19]
	v_mfma_f32_16x16x32_bf16 v[4:7], v[160:163], v[214:217], v[4:7]
	v_mfma_f32_16x16x32_bf16 v[0:3], v[176:179], v[214:217], v[0:3]
	v_mfma_f32_16x16x32_bf16 v[52:55], v[172:175], v[194:197], v[52:55]
	v_mfma_f32_16x16x32_bf16 v[48:51], v[180:183], v[194:197], v[48:51]
	v_mfma_f32_16x16x32_bf16 v[36:39], v[172:175], v[202:205], v[36:39]
	v_mfma_f32_16x16x32_bf16 v[32:35], v[180:183], v[202:205], v[32:35]
	v_mfma_f32_16x16x32_bf16 v[20:23], v[172:175], v[210:213], v[20:23]
	v_mfma_f32_16x16x32_bf16 v[16:19], v[180:183], v[210:213], v[16:19]
	v_mfma_f32_16x16x32_bf16 v[4:7], v[172:175], v[218:221], v[4:7]
	v_mfma_f32_16x16x32_bf16 v[0:3], v[180:183], v[218:221], v[0:3]
	s_setprio 0
	s_barrier
	s_add_i32 s82, 0, 0x18000
	s_add_i32 s83, 0, 0x1c000
	v_add_u32_e32 v118, s82, v167
	v_add_u32_e32 v166, s83, v167
	ds_read_b128 v[102:105], v118
	ds_read_b128 v[110:113], v118 offset:1024
	ds_read_b128 v[114:117], v118 offset:2048
	ds_read_b128 v[118:121], v118 offset:3072
	ds_read_b128 v[160:163], v166
	ds_read_b128 v[172:175], v166 offset:1024
	ds_read_b128 v[176:179], v166 offset:2048
	ds_read_b128 v[180:183], v166 offset:3072
	s_add_u32 s68, s68, 0x40000
	s_addc_u32 s69, s69, 0
	s_mov_b32 m0, s19
	v_lshl_add_u64 v[224:225], s[68:69], 0, v[146:147]
	ds_read_b128 v[190:193], v171 offset:32768
	ds_read_b128 v[194:197], v171 offset:33792
	ds_read_b128 v[198:201], v171 offset:34816
	ds_read_b128 v[202:205], v171 offset:35840
	ds_read_b128 v[206:209], v171 offset:36864
	ds_read_b128 v[210:213], v171 offset:37888
	ds_read_b128 v[214:217], v171 offset:38912
	ds_read_b128 v[218:221], v171 offset:39936
	global_load_lds_dwordx4 v[224:225], off
	v_lshl_add_u64 v[224:225], s[68:69], 0, v[150:151]
	s_mov_b32 m0, s34
	s_nop 0
	global_load_lds_dwordx4 v[224:225], off
	s_waitcnt vmcnt(8)
	s_waitcnt lgkmcnt(0)
	s_barrier
	s_setprio 1
	v_mfma_f32_16x16x32_bf16 v[142:145], v[102:105], v[190:193], v[142:145]
	v_mfma_f32_16x16x32_bf16 v[138:141], v[114:117], v[190:193], v[138:141]
	v_mfma_f32_16x16x32_bf16 v[126:129], v[102:105], v[198:201], v[126:129]
	v_mfma_f32_16x16x32_bf16 v[122:125], v[114:117], v[198:201], v[122:125]
	v_mfma_f32_16x16x32_bf16 v[94:97], v[102:105], v[206:209], v[94:97]
	v_mfma_f32_16x16x32_bf16 v[90:93], v[114:117], v[206:209], v[90:93]
	v_mfma_f32_16x16x32_bf16 v[78:81], v[102:105], v[214:217], v[78:81]
	v_mfma_f32_16x16x32_bf16 v[74:77], v[114:117], v[214:217], v[74:77]
	v_mfma_f32_16x16x32_bf16 v[142:145], v[110:113], v[194:197], v[142:145]
	v_mfma_f32_16x16x32_bf16 v[138:141], v[118:121], v[194:197], v[138:141]
	v_mfma_f32_16x16x32_bf16 v[126:129], v[110:113], v[202:205], v[126:129]
	v_mfma_f32_16x16x32_bf16 v[122:125], v[118:121], v[202:205], v[122:125]
	v_mfma_f32_16x16x32_bf16 v[94:97], v[110:113], v[210:213], v[94:97]
	v_mfma_f32_16x16x32_bf16 v[90:93], v[118:121], v[210:213], v[90:93]
	v_mfma_f32_16x16x32_bf16 v[78:81], v[110:113], v[218:221], v[78:81]
	v_mfma_f32_16x16x32_bf16 v[74:77], v[118:121], v[218:221], v[74:77]
	v_mfma_f32_16x16x32_bf16 v[134:137], v[160:163], v[190:193], v[134:137]
	v_mfma_f32_16x16x32_bf16 v[130:133], v[176:179], v[190:193], v[130:133]
	v_mfma_f32_16x16x32_bf16 v[106:109], v[160:163], v[198:201], v[106:109]
	v_mfma_f32_16x16x32_bf16 v[98:101], v[176:179], v[198:201], v[98:101]
	v_mfma_f32_16x16x32_bf16 v[86:89], v[160:163], v[206:209], v[86:89]
	v_mfma_f32_16x16x32_bf16 v[82:85], v[176:179], v[206:209], v[82:85]
	v_mfma_f32_16x16x32_bf16 v[70:73], v[160:163], v[214:217], v[70:73]
	v_mfma_f32_16x16x32_bf16 v[66:69], v[176:179], v[214:217], v[66:69]
	v_mfma_f32_16x16x32_bf16 v[134:137], v[172:175], v[194:197], v[134:137]
	v_mfma_f32_16x16x32_bf16 v[130:133], v[180:183], v[194:197], v[130:133]
	v_mfma_f32_16x16x32_bf16 v[106:109], v[172:175], v[202:205], v[106:109]
	v_mfma_f32_16x16x32_bf16 v[98:101], v[180:183], v[202:205], v[98:101]
	v_mfma_f32_16x16x32_bf16 v[86:89], v[172:175], v[210:213], v[86:89]
	v_mfma_f32_16x16x32_bf16 v[82:85], v[180:183], v[210:213], v[82:85]
	v_mfma_f32_16x16x32_bf16 v[70:73], v[172:175], v[218:221], v[70:73]
	v_mfma_f32_16x16x32_bf16 v[66:69], v[180:183], v[218:221], v[66:69]
	s_setprio 0
	s_barrier
	s_add_i32 s68, s82, s10
	v_lshl_add_u64 v[164:165], v[164:165], 0, s[16:17]
	s_mov_b32 m0, s68
	ds_read_b128 v[190:193], v171 offset:49152
	ds_read_b128 v[194:197], v171 offset:50176
	ds_read_b128 v[198:201], v171 offset:51200
	ds_read_b128 v[202:205], v171 offset:52224
	ds_read_b128 v[206:209], v171 offset:53248
	ds_read_b128 v[210:213], v171 offset:54272
	ds_read_b128 v[214:217], v171 offset:55296
	ds_read_b128 v[218:221], v171 offset:56320
	global_load_lds_dwordx4 v[164:165], off
	s_add_i32 m0, s68, 0x2000
	s_add_u32 s30, s30, 0x40080
	v_lshl_add_u64 v[164:165], v[168:169], 0, s[16:17]
	s_addc_u32 s31, s31, 0
	s_add_i32 s68, s83, s10
	global_load_lds_dwordx4 v[164:165], off
	v_lshl_add_u64 v[164:165], s[30:31], 0, v[148:149]
	s_mov_b32 m0, s68
	s_nop 0
	global_load_lds_dwordx4 v[164:165], off
	v_lshl_add_u64 v[164:165], s[30:31], 0, v[152:153]
	s_add_i32 m0, s68, 0x2000
	s_nop 0
	global_load_lds_dwordx4 v[164:165], off
	v_lshl_add_u64 v[164:165], v[184:185], 0, s[16:17]
	s_mov_b32 m0, s46
	s_nop 0
	global_load_lds_dwordx4 v[164:165], off
	v_lshl_add_u64 v[164:165], v[222:223], 0, s[16:17]
	s_mov_b32 m0, s47
	s_nop 0
	global_load_lds_dwordx4 v[164:165], off
	s_waitcnt vmcnt(8)
	s_waitcnt lgkmcnt(0)
	s_barrier
	s_setprio 1
	v_mfma_f32_16x16x32_bf16 v[60:63], v[102:105], v[190:193], v[60:63]
	v_mfma_f32_16x16x32_bf16 v[56:59], v[114:117], v[190:193], v[56:59]
	v_mfma_f32_16x16x32_bf16 v[44:47], v[102:105], v[198:201], v[44:47]
	v_mfma_f32_16x16x32_bf16 v[40:43], v[114:117], v[198:201], v[40:43]
	v_mfma_f32_16x16x32_bf16 v[28:31], v[102:105], v[206:209], v[28:31]
	v_mfma_f32_16x16x32_bf16 v[24:27], v[114:117], v[206:209], v[24:27]
	v_mfma_f32_16x16x32_bf16 v[12:15], v[102:105], v[214:217], v[12:15]
	v_mfma_f32_16x16x32_bf16 v[8:11], v[114:117], v[214:217], v[8:11]
	v_mfma_f32_16x16x32_bf16 v[60:63], v[110:113], v[194:197], v[60:63]
	v_mfma_f32_16x16x32_bf16 v[56:59], v[118:121], v[194:197], v[56:59]
	v_mfma_f32_16x16x32_bf16 v[44:47], v[110:113], v[202:205], v[44:47]
	v_mfma_f32_16x16x32_bf16 v[40:43], v[118:121], v[202:205], v[40:43]
	v_mfma_f32_16x16x32_bf16 v[28:31], v[110:113], v[210:213], v[28:31]
	v_mfma_f32_16x16x32_bf16 v[24:27], v[118:121], v[210:213], v[24:27]
	v_mfma_f32_16x16x32_bf16 v[12:15], v[110:113], v[218:221], v[12:15]
	v_mfma_f32_16x16x32_bf16 v[8:11], v[118:121], v[218:221], v[8:11]
	v_mfma_f32_16x16x32_bf16 v[52:55], v[160:163], v[190:193], v[52:55]
	v_mfma_f32_16x16x32_bf16 v[48:51], v[176:179], v[190:193], v[48:51]
	v_mfma_f32_16x16x32_bf16 v[36:39], v[160:163], v[198:201], v[36:39]
	v_mfma_f32_16x16x32_bf16 v[32:35], v[176:179], v[198:201], v[32:35]
	v_mfma_f32_16x16x32_bf16 v[20:23], v[160:163], v[206:209], v[20:23]
	v_mfma_f32_16x16x32_bf16 v[16:19], v[176:179], v[206:209], v[16:19]
	v_mfma_f32_16x16x32_bf16 v[4:7], v[160:163], v[214:217], v[4:7]
	v_mfma_f32_16x16x32_bf16 v[0:3], v[176:179], v[214:217], v[0:3]
	v_mfma_f32_16x16x32_bf16 v[52:55], v[172:175], v[194:197], v[52:55]
	v_mfma_f32_16x16x32_bf16 v[48:51], v[180:183], v[194:197], v[48:51]
	v_mfma_f32_16x16x32_bf16 v[36:39], v[172:175], v[202:205], v[36:39]
	v_mfma_f32_16x16x32_bf16 v[32:35], v[180:183], v[202:205], v[32:35]
	v_mfma_f32_16x16x32_bf16 v[20:23], v[172:175], v[210:213], v[20:23]
	v_mfma_f32_16x16x32_bf16 v[16:19], v[180:183], v[210:213], v[16:19]
	v_mfma_f32_16x16x32_bf16 v[4:7], v[172:175], v[218:221], v[4:7]
	v_mfma_f32_16x16x32_bf16 v[0:3], v[180:183], v[218:221], v[0:3]
	s_setprio 0
	s_add_i32 s77, s77, 2
	s_add_u32 s28, s28, 0x100
	s_addc_u32 s29, s29, 0
	s_add_u32 s75, s75, 0x100
	s_addc_u32 s76, s76, 0
	s_cmp_gt_u32 s77, 13
	s_barrier
	s_cbranch_scc0 .LBB0_790
	s_and_b64 vcc, exec, s[42:43]
	s_cbranch_vccz .LBB0_793
	s_barrier

.LBB0_893:
	s_add_u32 s30, s28, 0xfffc0080
	s_addc_u32 s31, s29, -1
	s_add_i32 s84, 0, 0x10000
	s_cmp_eq_u32 s83, 12
	s_cselect_b32 s69, s63, s31
	s_cselect_b32 s68, s75, s30
	s_cselect_b32 s31, s45, s82
	s_cselect_b32 s30, s76, s77
	s_add_i32 s85, 0, 0x14000
	v_add_u32_e32 v110, s84, v167
	v_add_u32_e32 v164, s85, v167
	ds_read_b128 v[98:101], v110
	ds_read_b128 v[102:105], v110 offset:1024
	ds_read_b128 v[106:109], v110 offset:2048
	ds_read_b128 v[110:113], v110 offset:3072
	ds_read_b128 v[160:163], v164
	ds_read_b128 v[172:175], v164 offset:1024
	ds_read_b128 v[176:179], v164 offset:2048
	ds_read_b128 v[180:183], v164 offset:3072
	v_lshl_add_u64 v[164:165], s[28:29], 0, v[156:157]
	s_add_i32 m0, s11, 0xc000
	ds_read_b128 v[190:193], v171
	ds_read_b128 v[194:197], v171 offset:1024
	ds_read_b128 v[198:201], v171 offset:2048
	ds_read_b128 v[202:205], v171 offset:3072
	ds_read_b128 v[206:209], v171 offset:4096
	ds_read_b128 v[210:213], v171 offset:5120
	ds_read_b128 v[214:217], v171 offset:6144
	ds_read_b128 v[218:221], v171 offset:7168
	global_load_lds_dwordx4 v[164:165], off
	v_lshl_add_u64 v[164:165], s[28:29], 0, v[158:159]
	s_add_i32 m0, s11, 0xe000
	s_nop 0
	global_load_lds_dwordx4 v[164:165], off
	s_waitcnt vmcnt(8)
	s_waitcnt lgkmcnt(0)
	s_barrier
	s_setprio 1
	v_mfma_f32_16x16x32_bf16 v[142:145], v[98:101], v[190:193], v[142:145]
	v_mfma_f32_16x16x32_bf16 v[138:141], v[106:109], v[190:193], v[138:141]
	v_mfma_f32_16x16x32_bf16 v[126:129], v[98:101], v[198:201], v[126:129]
	v_mfma_f32_16x16x32_bf16 v[122:125], v[106:109], v[198:201], v[122:125]
	v_mfma_f32_16x16x32_bf16 v[94:97], v[98:101], v[206:209], v[94:97]
	v_mfma_f32_16x16x32_bf16 v[90:93], v[106:109], v[206:209], v[90:93]
	v_mfma_f32_16x16x32_bf16 v[78:81], v[98:101], v[214:217], v[78:81]
	v_mfma_f32_16x16x32_bf16 v[74:77], v[106:109], v[214:217], v[74:77]
	v_mfma_f32_16x16x32_bf16 v[142:145], v[102:105], v[194:197], v[142:145]
	v_mfma_f32_16x16x32_bf16 v[138:141], v[110:113], v[194:197], v[138:141]
	v_mfma_f32_16x16x32_bf16 v[126:129], v[102:105], v[202:205], v[126:129]
	v_mfma_f32_16x16x32_bf16 v[122:125], v[110:113], v[202:205], v[122:125]
	v_mfma_f32_16x16x32_bf16 v[94:97], v[102:105], v[210:213], v[94:97]
	v_mfma_f32_16x16x32_bf16 v[90:93], v[110:113], v[210:213], v[90:93]
	v_mfma_f32_16x16x32_bf16 v[78:81], v[102:105], v[218:221], v[78:81]
	v_mfma_f32_16x16x32_bf16 v[74:77], v[110:113], v[218:221], v[74:77]
	v_mfma_f32_16x16x32_bf16 v[134:137], v[160:163], v[190:193], v[134:137]
	v_mfma_f32_16x16x32_bf16 v[130:133], v[176:179], v[190:193], v[130:133]
	v_mfma_f32_16x16x32_bf16 v[118:121], v[160:163], v[198:201], v[118:121]
	v_mfma_f32_16x16x32_bf16 v[114:117], v[176:179], v[198:201], v[114:117]
	v_mfma_f32_16x16x32_bf16 v[86:89], v[160:163], v[206:209], v[86:89]
	v_mfma_f32_16x16x32_bf16 v[82:85], v[176:179], v[206:209], v[82:85]
	v_mfma_f32_16x16x32_bf16 v[70:73], v[160:163], v[214:217], v[70:73]
	v_mfma_f32_16x16x32_bf16 v[66:69], v[176:179], v[214:217], v[66:69]
	v_mfma_f32_16x16x32_bf16 v[134:137], v[172:175], v[194:197], v[134:137]
	v_mfma_f32_16x16x32_bf16 v[130:133], v[180:183], v[194:197], v[130:133]
	v_mfma_f32_16x16x32_bf16 v[118:121], v[172:175], v[202:205], v[118:121]
	v_mfma_f32_16x16x32_bf16 v[114:117], v[180:183], v[202:205], v[114:117]
	v_mfma_f32_16x16x32_bf16 v[86:89], v[172:175], v[210:213], v[86:89]
	v_mfma_f32_16x16x32_bf16 v[82:85], v[180:183], v[210:213], v[82:85]
	v_mfma_f32_16x16x32_bf16 v[70:73], v[172:175], v[218:221], v[70:73]
	v_mfma_f32_16x16x32_bf16 v[66:69], v[180:183], v[218:221], v[66:69]
	s_setprio 0
	s_barrier
	s_add_i32 s84, s84, s10
	v_lshl_add_u64 v[164:165], s[30:31], 0, v[148:149]
	s_mov_b32 m0, s84
	ds_read_b128 v[190:193], v171 offset:16384
	ds_read_b128 v[194:197], v171 offset:17408
	ds_read_b128 v[198:201], v171 offset:18432
	ds_read_b128 v[202:205], v171 offset:19456
	ds_read_b128 v[206:209], v171 offset:20480
	ds_read_b128 v[210:213], v171 offset:21504
	ds_read_b128 v[214:217], v171 offset:22528
	ds_read_b128 v[218:221], v171 offset:23552
	global_load_lds_dwordx4 v[164:165], off
	s_add_i32 m0, s84, 0x2000
	s_add_u32 s90, s30, 0x40000
	v_lshl_add_u64 v[168:169], s[30:31], 0, v[152:153]
	s_addc_u32 s91, s31, 0
	s_add_i32 s84, s85, s10
	global_load_lds_dwordx4 v[168:169], off
	v_lshl_add_u64 v[184:185], s[90:91], 0, v[148:149]
	s_mov_b32 m0, s84
	v_lshl_add_u64 v[222:223], s[68:69], 0, v[150:151]
	global_load_lds_dwordx4 v[184:185], off
	v_lshl_add_u64 v[184:185], s[90:91], 0, v[152:153]
	s_add_i32 m0, s84, 0x2000
	s_nop 0
	global_load_lds_dwordx4 v[184:185], off
	v_lshl_add_u64 v[184:185], s[68:69], 0, v[146:147]
	s_mov_b32 m0, s11
	s_nop 0
	global_load_lds_dwordx4 v[184:185], off
	s_mov_b32 m0, s13
	s_nop 0
	global_load_lds_dwordx4 v[222:223], off
	s_waitcnt vmcnt(8)
	s_waitcnt lgkmcnt(0)
	s_barrier
	s_setprio 1
	v_mfma_f32_16x16x32_bf16 v[60:63], v[98:101], v[190:193], v[60:63]
	v_mfma_f32_16x16x32_bf16 v[56:59], v[106:109], v[190:193], v[56:59]
	v_mfma_f32_16x16x32_bf16 v[44:47], v[98:101], v[198:201], v[44:47]
	v_mfma_f32_16x16x32_bf16 v[40:43], v[106:109], v[198:201], v[40:43]
	v_mfma_f32_16x16x32_bf16 v[28:31], v[98:101], v[206:209], v[28:31]
	v_mfma_f32_16x16x32_bf16 v[24:27], v[106:109], v[206:209], v[24:27]
	v_mfma_f32_16x16x32_bf16 v[12:15], v[98:101], v[214:217], v[12:15]
	v_mfma_f32_16x16x32_bf16 v[8:11], v[106:109], v[214:217], v[8:11]
	v_mfma_f32_16x16x32_bf16 v[60:63], v[102:105], v[194:197], v[60:63]
	v_mfma_f32_16x16x32_bf16 v[56:59], v[110:113], v[194:197], v[56:59]
	v_mfma_f32_16x16x32_bf16 v[44:47], v[102:105], v[202:205], v[44:47]
	v_mfma_f32_16x16x32_bf16 v[40:43], v[110:113], v[202:205], v[40:43]
	v_mfma_f32_16x16x32_bf16 v[28:31], v[102:105], v[210:213], v[28:31]
	v_mfma_f32_16x16x32_bf16 v[24:27], v[110:113], v[210:213], v[24:27]
	v_mfma_f32_16x16x32_bf16 v[12:15], v[102:105], v[218:221], v[12:15]
	v_mfma_f32_16x16x32_bf16 v[8:11], v[110:113], v[218:221], v[8:11]
	v_mfma_f32_16x16x32_bf16 v[52:55], v[160:163], v[190:193], v[52:55]
	v_mfma_f32_16x16x32_bf16 v[48:51], v[176:179], v[190:193], v[48:51]
	v_mfma_f32_16x16x32_bf16 v[36:39], v[160:163], v[198:201], v[36:39]
	v_mfma_f32_16x16x32_bf16 v[32:35], v[176:179], v[198:201], v[32:35]
	v_mfma_f32_16x16x32_bf16 v[20:23], v[160:163], v[206:209], v[20:23]
	v_mfma_f32_16x16x32_bf16 v[16:19], v[176:179], v[206:209], v[16:19]
	v_mfma_f32_16x16x32_bf16 v[4:7], v[160:163], v[214:217], v[4:7]
	v_mfma_f32_16x16x32_bf16 v[0:3], v[176:179], v[214:217], v[0:3]
	v_mfma_f32_16x16x32_bf16 v[52:55], v[172:175], v[194:197], v[52:55]
	v_mfma_f32_16x16x32_bf16 v[48:51], v[180:183], v[194:197], v[48:51]
	v_mfma_f32_16x16x32_bf16 v[36:39], v[172:175], v[202:205], v[36:39]
	v_mfma_f32_16x16x32_bf16 v[32:35], v[180:183], v[202:205], v[32:35]
	v_mfma_f32_16x16x32_bf16 v[20:23], v[172:175], v[210:213], v[20:23]
	v_mfma_f32_16x16x32_bf16 v[16:19], v[180:183], v[210:213], v[16:19]
	v_mfma_f32_16x16x32_bf16 v[4:7], v[172:175], v[218:221], v[4:7]
	v_mfma_f32_16x16x32_bf16 v[0:3], v[180:183], v[218:221], v[0:3]
	s_setprio 0
	s_barrier
	s_add_i32 s84, 0, 0x18000
	s_add_i32 s85, 0, 0x1c000
	v_add_u32_e32 v110, s84, v167
	v_add_u32_e32 v166, s85, v167
	ds_read_b128 v[98:101], v110
	ds_read_b128 v[102:105], v110 offset:1024
	ds_read_b128 v[106:109], v110 offset:2048
	ds_read_b128 v[110:113], v110 offset:3072
	ds_read_b128 v[160:163], v166
	ds_read_b128 v[172:175], v166 offset:1024
	ds_read_b128 v[176:179], v166 offset:2048
	ds_read_b128 v[180:183], v166 offset:3072
	s_add_u32 s68, s68, 0x40000
	s_addc_u32 s69, s69, 0
	s_mov_b32 m0, s19
	v_lshl_add_u64 v[224:225], s[68:69], 0, v[146:147]
	ds_read_b128 v[190:193], v171 offset:32768
	ds_read_b128 v[194:197], v171 offset:33792
	ds_read_b128 v[198:201], v171 offset:34816
	ds_read_b128 v[202:205], v171 offset:35840
	ds_read_b128 v[206:209], v171 offset:36864
	ds_read_b128 v[210:213], v171 offset:37888
	ds_read_b128 v[214:217], v171 offset:38912
	ds_read_b128 v[218:221], v171 offset:39936
	global_load_lds_dwordx4 v[224:225], off
	v_lshl_add_u64 v[224:225], s[68:69], 0, v[150:151]
	s_mov_b32 m0, s34
	s_nop 0
	global_load_lds_dwordx4 v[224:225], off
	s_waitcnt vmcnt(8)
	s_waitcnt lgkmcnt(0)
	s_barrier
	s_setprio 1
	v_mfma_f32_16x16x32_bf16 v[142:145], v[98:101], v[190:193], v[142:145]
	v_mfma_f32_16x16x32_bf16 v[138:141], v[106:109], v[190:193], v[138:141]
	v_mfma_f32_16x16x32_bf16 v[126:129], v[98:101], v[198:201], v[126:129]
	v_mfma_f32_16x16x32_bf16 v[122:125], v[106:109], v[198:201], v[122:125]
	v_mfma_f32_16x16x32_bf16 v[94:97], v[98:101], v[206:209], v[94:97]
	v_mfma_f32_16x16x32_bf16 v[90:93], v[106:109], v[206:209], v[90:93]
	v_mfma_f32_16x16x32_bf16 v[78:81], v[98:101], v[214:217], v[78:81]
	v_mfma_f32_16x16x32_bf16 v[74:77], v[106:109], v[214:217], v[74:77]
	v_mfma_f32_16x16x32_bf16 v[142:145], v[102:105], v[194:197], v[142:145]
	v_mfma_f32_16x16x32_bf16 v[138:141], v[110:113], v[194:197], v[138:141]
	v_mfma_f32_16x16x32_bf16 v[126:129], v[102:105], v[202:205], v[126:129]
	v_mfma_f32_16x16x32_bf16 v[122:125], v[110:113], v[202:205], v[122:125]
	v_mfma_f32_16x16x32_bf16 v[94:97], v[102:105], v[210:213], v[94:97]
	v_mfma_f32_16x16x32_bf16 v[90:93], v[110:113], v[210:213], v[90:93]
	v_mfma_f32_16x16x32_bf16 v[78:81], v[102:105], v[218:221], v[78:81]
	v_mfma_f32_16x16x32_bf16 v[74:77], v[110:113], v[218:221], v[74:77]
	v_mfma_f32_16x16x32_bf16 v[134:137], v[160:163], v[190:193], v[134:137]
	v_mfma_f32_16x16x32_bf16 v[130:133], v[176:179], v[190:193], v[130:133]
	v_mfma_f32_16x16x32_bf16 v[118:121], v[160:163], v[198:201], v[118:121]
	v_mfma_f32_16x16x32_bf16 v[114:117], v[176:179], v[198:201], v[114:117]
	v_mfma_f32_16x16x32_bf16 v[86:89], v[160:163], v[206:209], v[86:89]
	v_mfma_f32_16x16x32_bf16 v[82:85], v[176:179], v[206:209], v[82:85]
	v_mfma_f32_16x16x32_bf16 v[70:73], v[160:163], v[214:217], v[70:73]
	v_mfma_f32_16x16x32_bf16 v[66:69], v[176:179], v[214:217], v[66:69]
	v_mfma_f32_16x16x32_bf16 v[134:137], v[172:175], v[194:197], v[134:137]
	v_mfma_f32_16x16x32_bf16 v[130:133], v[180:183], v[194:197], v[130:133]
	v_mfma_f32_16x16x32_bf16 v[118:121], v[172:175], v[202:205], v[118:121]
	v_mfma_f32_16x16x32_bf16 v[114:117], v[180:183], v[202:205], v[114:117]
	v_mfma_f32_16x16x32_bf16 v[86:89], v[172:175], v[210:213], v[86:89]
	v_mfma_f32_16x16x32_bf16 v[82:85], v[180:183], v[210:213], v[82:85]
	v_mfma_f32_16x16x32_bf16 v[70:73], v[172:175], v[218:221], v[70:73]
	v_mfma_f32_16x16x32_bf16 v[66:69], v[180:183], v[218:221], v[66:69]
	s_setprio 0
	s_barrier
	s_add_i32 s68, s84, s10
	v_lshl_add_u64 v[164:165], v[164:165], 0, s[16:17]
	s_mov_b32 m0, s68
	ds_read_b128 v[190:193], v171 offset:49152
	ds_read_b128 v[194:197], v171 offset:50176
	ds_read_b128 v[198:201], v171 offset:51200
	ds_read_b128 v[202:205], v171 offset:52224
	ds_read_b128 v[206:209], v171 offset:53248
	ds_read_b128 v[210:213], v171 offset:54272
	ds_read_b128 v[214:217], v171 offset:55296
	ds_read_b128 v[218:221], v171 offset:56320
	global_load_lds_dwordx4 v[164:165], off
	s_add_i32 m0, s68, 0x2000
	s_add_u32 s30, s30, 0x40080
	v_lshl_add_u64 v[164:165], v[168:169], 0, s[16:17]
	s_addc_u32 s31, s31, 0
	s_add_i32 s68, s85, s10
	global_load_lds_dwordx4 v[164:165], off
	v_lshl_add_u64 v[164:165], s[30:31], 0, v[148:149]
	s_mov_b32 m0, s68
	s_nop 0
	global_load_lds_dwordx4 v[164:165], off
	v_lshl_add_u64 v[164:165], s[30:31], 0, v[152:153]
	s_add_i32 m0, s68, 0x2000
	s_nop 0
	global_load_lds_dwordx4 v[164:165], off
	v_lshl_add_u64 v[164:165], v[184:185], 0, s[16:17]
	s_mov_b32 m0, s61
	s_nop 0
	global_load_lds_dwordx4 v[164:165], off
	v_lshl_add_u64 v[164:165], v[222:223], 0, s[16:17]
	s_mov_b32 m0, s70
	s_nop 0
	global_load_lds_dwordx4 v[164:165], off
	s_waitcnt vmcnt(8)
	s_waitcnt lgkmcnt(0)
	s_barrier
	s_setprio 1
	v_mfma_f32_16x16x32_bf16 v[60:63], v[98:101], v[190:193], v[60:63]
	v_mfma_f32_16x16x32_bf16 v[56:59], v[106:109], v[190:193], v[56:59]
	v_mfma_f32_16x16x32_bf16 v[44:47], v[98:101], v[198:201], v[44:47]
	v_mfma_f32_16x16x32_bf16 v[40:43], v[106:109], v[198:201], v[40:43]
	v_mfma_f32_16x16x32_bf16 v[28:31], v[98:101], v[206:209], v[28:31]
	v_mfma_f32_16x16x32_bf16 v[24:27], v[106:109], v[206:209], v[24:27]
	v_mfma_f32_16x16x32_bf16 v[12:15], v[98:101], v[214:217], v[12:15]
	v_mfma_f32_16x16x32_bf16 v[8:11], v[106:109], v[214:217], v[8:11]
	v_mfma_f32_16x16x32_bf16 v[60:63], v[102:105], v[194:197], v[60:63]
	v_mfma_f32_16x16x32_bf16 v[56:59], v[110:113], v[194:197], v[56:59]
	v_mfma_f32_16x16x32_bf16 v[44:47], v[102:105], v[202:205], v[44:47]
	v_mfma_f32_16x16x32_bf16 v[40:43], v[110:113], v[202:205], v[40:43]
	v_mfma_f32_16x16x32_bf16 v[28:31], v[102:105], v[210:213], v[28:31]
	v_mfma_f32_16x16x32_bf16 v[24:27], v[110:113], v[210:213], v[24:27]
	v_mfma_f32_16x16x32_bf16 v[12:15], v[102:105], v[218:221], v[12:15]
	v_mfma_f32_16x16x32_bf16 v[8:11], v[110:113], v[218:221], v[8:11]
	v_mfma_f32_16x16x32_bf16 v[52:55], v[160:163], v[190:193], v[52:55]
	v_mfma_f32_16x16x32_bf16 v[48:51], v[176:179], v[190:193], v[48:51]
	v_mfma_f32_16x16x32_bf16 v[36:39], v[160:163], v[198:201], v[36:39]
	v_mfma_f32_16x16x32_bf16 v[32:35], v[176:179], v[198:201], v[32:35]
	v_mfma_f32_16x16x32_bf16 v[20:23], v[160:163], v[206:209], v[20:23]
	v_mfma_f32_16x16x32_bf16 v[16:19], v[176:179], v[206:209], v[16:19]
	v_mfma_f32_16x16x32_bf16 v[4:7], v[160:163], v[214:217], v[4:7]
	v_mfma_f32_16x16x32_bf16 v[0:3], v[176:179], v[214:217], v[0:3]
	v_mfma_f32_16x16x32_bf16 v[52:55], v[172:175], v[194:197], v[52:55]
	v_mfma_f32_16x16x32_bf16 v[48:51], v[180:183], v[194:197], v[48:51]
	v_mfma_f32_16x16x32_bf16 v[36:39], v[172:175], v[202:205], v[36:39]
	v_mfma_f32_16x16x32_bf16 v[32:35], v[180:183], v[202:205], v[32:35]
	v_mfma_f32_16x16x32_bf16 v[20:23], v[172:175], v[210:213], v[20:23]
	v_mfma_f32_16x16x32_bf16 v[16:19], v[180:183], v[210:213], v[16:19]
	v_mfma_f32_16x16x32_bf16 v[4:7], v[172:175], v[218:221], v[4:7]
	v_mfma_f32_16x16x32_bf16 v[0:3], v[180:183], v[218:221], v[0:3]
	s_setprio 0
	s_add_i32 s83, s83, 2
	s_add_u32 s28, s28, 0x100
	s_addc_u32 s29, s29, 0
	s_add_u32 s77, s77, 0x100
	s_addc_u32 s82, s82, 0
	s_cmp_gt_u32 s83, 13
	s_barrier
	s_cbranch_scc0 .LBB0_893
	s_and_b64 vcc, exec, s[42:43]
	s_cbranch_vccz .LBB0_896
	s_barrier

.LBB0_1250:
	s_add_u32 s30, s28, 0xfffc0080
	s_addc_u32 s31, s29, -1
	s_add_i32 s75, 0, 0x10000
	s_cmp_eq_u32 s74, 12
	s_cselect_b32 s69, s63, s31
	s_cselect_b32 s68, s70, s30
	s_cselect_b32 s31, s49, s73
	s_cselect_b32 s30, s71, s72
	s_add_i32 s83, 0, 0x14000
	v_add_u32_e32 v110, s75, v223
	v_add_u32_e32 v170, s83, v223
	ds_read_b128 v[98:101], v110
	ds_read_b128 v[102:105], v110 offset:1024
	ds_read_b128 v[106:109], v110 offset:2048
	ds_read_b128 v[110:113], v110 offset:3072
	ds_read_b128 v[146:149], v170
	ds_read_b128 v[162:165], v170 offset:1024
	ds_read_b128 v[166:169], v170 offset:2048
	ds_read_b128 v[170:173], v170 offset:3072
	v_lshl_add_u64 v[210:211], s[28:29], 0, v[158:159]
	s_add_i32 m0, s0, 0xc000
	ds_read_b128 v[174:177], v225
	ds_read_b128 v[178:181], v225 offset:1024
	ds_read_b128 v[182:185], v225 offset:2048
	ds_read_b128 v[190:193], v225 offset:3072
	ds_read_b128 v[194:197], v225 offset:4096
	ds_read_b128 v[198:201], v225 offset:5120
	ds_read_b128 v[202:205], v225 offset:6144
	ds_read_b128 v[206:209], v225 offset:7168
	global_load_lds_dwordx4 v[210:211], off
	v_lshl_add_u64 v[210:211], s[28:29], 0, v[160:161]
	s_add_i32 m0, s0, 0xe000
	s_nop 0
	global_load_lds_dwordx4 v[210:211], off
	s_waitcnt vmcnt(8)
	s_waitcnt lgkmcnt(0)
	s_barrier
	s_setprio 1
	v_mfma_f32_16x16x32_bf16 v[142:145], v[98:101], v[174:177], v[142:145]
	v_mfma_f32_16x16x32_bf16 v[138:141], v[106:109], v[174:177], v[138:141]
	v_mfma_f32_16x16x32_bf16 v[134:137], v[98:101], v[182:185], v[134:137]
	v_mfma_f32_16x16x32_bf16 v[130:133], v[106:109], v[182:185], v[130:133]
	v_mfma_f32_16x16x32_bf16 v[126:129], v[98:101], v[194:197], v[126:129]
	v_mfma_f32_16x16x32_bf16 v[122:125], v[106:109], v[194:197], v[122:125]
	v_mfma_f32_16x16x32_bf16 v[118:121], v[98:101], v[202:205], v[118:121]
	v_mfma_f32_16x16x32_bf16 v[114:117], v[106:109], v[202:205], v[114:117]
	v_mfma_f32_16x16x32_bf16 v[142:145], v[102:105], v[178:181], v[142:145]
	v_mfma_f32_16x16x32_bf16 v[138:141], v[110:113], v[178:181], v[138:141]
	v_mfma_f32_16x16x32_bf16 v[134:137], v[102:105], v[190:193], v[134:137]
	v_mfma_f32_16x16x32_bf16 v[130:133], v[110:113], v[190:193], v[130:133]
	v_mfma_f32_16x16x32_bf16 v[126:129], v[102:105], v[198:201], v[126:129]
	v_mfma_f32_16x16x32_bf16 v[122:125], v[110:113], v[198:201], v[122:125]
	v_mfma_f32_16x16x32_bf16 v[118:121], v[102:105], v[206:209], v[118:121]
	v_mfma_f32_16x16x32_bf16 v[114:117], v[110:113], v[206:209], v[114:117]
	v_mfma_f32_16x16x32_bf16 v[60:63], v[146:149], v[174:177], v[60:63]
	v_mfma_f32_16x16x32_bf16 v[56:59], v[166:169], v[174:177], v[56:59]
	v_mfma_f32_16x16x32_bf16 v[52:55], v[146:149], v[182:185], v[52:55]
	v_mfma_f32_16x16x32_bf16 v[48:51], v[166:169], v[182:185], v[48:51]
	v_mfma_f32_16x16x32_bf16 v[44:47], v[146:149], v[194:197], v[44:47]
	v_mfma_f32_16x16x32_bf16 v[40:43], v[166:169], v[194:197], v[40:43]
	v_mfma_f32_16x16x32_bf16 v[36:39], v[146:149], v[202:205], v[36:39]
	v_mfma_f32_16x16x32_bf16 v[32:35], v[166:169], v[202:205], v[32:35]
	v_mfma_f32_16x16x32_bf16 v[60:63], v[162:165], v[178:181], v[60:63]
	v_mfma_f32_16x16x32_bf16 v[56:59], v[170:173], v[178:181], v[56:59]
	v_mfma_f32_16x16x32_bf16 v[52:55], v[162:165], v[190:193], v[52:55]
	v_mfma_f32_16x16x32_bf16 v[48:51], v[170:173], v[190:193], v[48:51]
	v_mfma_f32_16x16x32_bf16 v[44:47], v[162:165], v[198:201], v[44:47]
	v_mfma_f32_16x16x32_bf16 v[40:43], v[170:173], v[198:201], v[40:43]
	v_mfma_f32_16x16x32_bf16 v[36:39], v[162:165], v[206:209], v[36:39]
	v_mfma_f32_16x16x32_bf16 v[32:35], v[170:173], v[206:209], v[32:35]
	s_setprio 0
	s_barrier
	s_add_i32 s75, s75, s5
	v_lshl_add_u64 v[210:211], s[30:31], 0, v[152:153]
	s_mov_b32 m0, s75
	ds_read_b128 v[174:177], v225 offset:16384
	ds_read_b128 v[178:181], v225 offset:17408
	ds_read_b128 v[182:185], v225 offset:18432
	ds_read_b128 v[190:193], v225 offset:19456
	ds_read_b128 v[194:197], v225 offset:20480
	ds_read_b128 v[198:201], v225 offset:21504
	ds_read_b128 v[202:205], v225 offset:22528
	ds_read_b128 v[206:209], v225 offset:23552
	global_load_lds_dwordx4 v[210:211], off
	s_add_i32 m0, s75, 0x2000
	s_add_u32 vcc_lo, s30, 0x40000
	v_lshl_add_u64 v[212:213], s[30:31], 0, v[156:157]
	s_addc_u32 vcc_hi, s31, 0
	s_add_i32 s75, s83, s5
	global_load_lds_dwordx4 v[212:213], off
	v_lshl_add_u64 v[214:215], vcc, 0, v[152:153]
	s_mov_b32 m0, s75
	v_lshl_add_u64 v[216:217], s[68:69], 0, v[154:155]
	global_load_lds_dwordx4 v[214:215], off
	v_lshl_add_u64 v[214:215], vcc, 0, v[156:157]
	s_add_i32 m0, s75, 0x2000
	s_nop 0
	global_load_lds_dwordx4 v[214:215], off
	v_lshl_add_u64 v[214:215], s[68:69], 0, v[150:151]
	s_mov_b32 m0, s0
	s_nop 0
	global_load_lds_dwordx4 v[214:215], off
	s_mov_b32 m0, s1
	s_nop 0
	global_load_lds_dwordx4 v[216:217], off
	s_waitcnt vmcnt(8)
	s_waitcnt lgkmcnt(0)
	s_barrier
	s_setprio 1
	v_mfma_f32_16x16x32_bf16 v[94:97], v[98:101], v[174:177], v[94:97]
	v_mfma_f32_16x16x32_bf16 v[90:93], v[106:109], v[174:177], v[90:93]
	v_mfma_f32_16x16x32_bf16 v[86:89], v[98:101], v[182:185], v[86:89]
	v_mfma_f32_16x16x32_bf16 v[82:85], v[106:109], v[182:185], v[82:85]
	v_mfma_f32_16x16x32_bf16 v[78:81], v[98:101], v[194:197], v[78:81]
	v_mfma_f32_16x16x32_bf16 v[74:77], v[106:109], v[194:197], v[74:77]
	v_mfma_f32_16x16x32_bf16 v[70:73], v[98:101], v[202:205], v[70:73]
	v_mfma_f32_16x16x32_bf16 v[66:69], v[106:109], v[202:205], v[66:69]
	v_mfma_f32_16x16x32_bf16 v[94:97], v[102:105], v[178:181], v[94:97]
	v_mfma_f32_16x16x32_bf16 v[90:93], v[110:113], v[178:181], v[90:93]
	v_mfma_f32_16x16x32_bf16 v[86:89], v[102:105], v[190:193], v[86:89]
	v_mfma_f32_16x16x32_bf16 v[82:85], v[110:113], v[190:193], v[82:85]
	v_mfma_f32_16x16x32_bf16 v[78:81], v[102:105], v[198:201], v[78:81]
	v_mfma_f32_16x16x32_bf16 v[74:77], v[110:113], v[198:201], v[74:77]
	v_mfma_f32_16x16x32_bf16 v[70:73], v[102:105], v[206:209], v[70:73]
	v_mfma_f32_16x16x32_bf16 v[66:69], v[110:113], v[206:209], v[66:69]
	v_mfma_f32_16x16x32_bf16 v[28:31], v[146:149], v[174:177], v[28:31]
	v_mfma_f32_16x16x32_bf16 v[24:27], v[166:169], v[174:177], v[24:27]
	v_mfma_f32_16x16x32_bf16 v[20:23], v[146:149], v[182:185], v[20:23]
	v_mfma_f32_16x16x32_bf16 v[16:19], v[166:169], v[182:185], v[16:19]
	v_mfma_f32_16x16x32_bf16 v[12:15], v[146:149], v[194:197], v[12:15]
	v_mfma_f32_16x16x32_bf16 v[8:11], v[166:169], v[194:197], v[8:11]
	v_mfma_f32_16x16x32_bf16 v[4:7], v[146:149], v[202:205], v[4:7]
	v_mfma_f32_16x16x32_bf16 v[0:3], v[166:169], v[202:205], v[0:3]
	v_mfma_f32_16x16x32_bf16 v[28:31], v[162:165], v[178:181], v[28:31]
	v_mfma_f32_16x16x32_bf16 v[24:27], v[170:173], v[178:181], v[24:27]
	v_mfma_f32_16x16x32_bf16 v[20:23], v[162:165], v[190:193], v[20:23]
	v_mfma_f32_16x16x32_bf16 v[16:19], v[170:173], v[190:193], v[16:19]
	v_mfma_f32_16x16x32_bf16 v[12:15], v[162:165], v[198:201], v[12:15]
	v_mfma_f32_16x16x32_bf16 v[8:11], v[170:173], v[198:201], v[8:11]
	v_mfma_f32_16x16x32_bf16 v[4:7], v[162:165], v[206:209], v[4:7]
	v_mfma_f32_16x16x32_bf16 v[0:3], v[170:173], v[206:209], v[0:3]
	s_setprio 0
	s_barrier
	s_add_i32 s75, 0, 0x18000
	s_add_i32 s83, 0, 0x1c000
	v_add_u32_e32 v110, s75, v223
	v_add_u32_e32 v170, s83, v223
	ds_read_b128 v[98:101], v110
	ds_read_b128 v[102:105], v110 offset:1024
	ds_read_b128 v[106:109], v110 offset:2048
	ds_read_b128 v[110:113], v110 offset:3072
	ds_read_b128 v[146:149], v170
	ds_read_b128 v[162:165], v170 offset:1024
	ds_read_b128 v[166:169], v170 offset:2048
	ds_read_b128 v[170:173], v170 offset:3072
	s_add_u32 s68, s68, 0x40000
	s_addc_u32 s69, s69, 0
	s_mov_b32 m0, s10
	v_lshl_add_u64 v[218:219], s[68:69], 0, v[150:151]
	ds_read_b128 v[174:177], v225 offset:32768
	ds_read_b128 v[178:181], v225 offset:33792
	ds_read_b128 v[182:185], v225 offset:34816
	ds_read_b128 v[190:193], v225 offset:35840
	ds_read_b128 v[194:197], v225 offset:36864
	ds_read_b128 v[198:201], v225 offset:37888
	ds_read_b128 v[202:205], v225 offset:38912
	ds_read_b128 v[206:209], v225 offset:39936
	global_load_lds_dwordx4 v[218:219], off
	v_lshl_add_u64 v[218:219], s[68:69], 0, v[154:155]
	s_mov_b32 m0, s11
	s_nop 0
	global_load_lds_dwordx4 v[218:219], off
	s_waitcnt vmcnt(8)
	s_waitcnt lgkmcnt(0)
	s_barrier
	s_setprio 1
	v_mfma_f32_16x16x32_bf16 v[142:145], v[98:101], v[174:177], v[142:145]
	v_mfma_f32_16x16x32_bf16 v[138:141], v[106:109], v[174:177], v[138:141]
	v_mfma_f32_16x16x32_bf16 v[134:137], v[98:101], v[182:185], v[134:137]
	v_mfma_f32_16x16x32_bf16 v[130:133], v[106:109], v[182:185], v[130:133]
	v_mfma_f32_16x16x32_bf16 v[126:129], v[98:101], v[194:197], v[126:129]
	v_mfma_f32_16x16x32_bf16 v[122:125], v[106:109], v[194:197], v[122:125]
	v_mfma_f32_16x16x32_bf16 v[118:121], v[98:101], v[202:205], v[118:121]
	v_mfma_f32_16x16x32_bf16 v[114:117], v[106:109], v[202:205], v[114:117]
	v_mfma_f32_16x16x32_bf16 v[142:145], v[102:105], v[178:181], v[142:145]
	v_mfma_f32_16x16x32_bf16 v[138:141], v[110:113], v[178:181], v[138:141]
	v_mfma_f32_16x16x32_bf16 v[134:137], v[102:105], v[190:193], v[134:137]
	v_mfma_f32_16x16x32_bf16 v[130:133], v[110:113], v[190:193], v[130:133]
	v_mfma_f32_16x16x32_bf16 v[126:129], v[102:105], v[198:201], v[126:129]
	v_mfma_f32_16x16x32_bf16 v[122:125], v[110:113], v[198:201], v[122:125]
	v_mfma_f32_16x16x32_bf16 v[118:121], v[102:105], v[206:209], v[118:121]
	v_mfma_f32_16x16x32_bf16 v[114:117], v[110:113], v[206:209], v[114:117]
	v_mfma_f32_16x16x32_bf16 v[60:63], v[146:149], v[174:177], v[60:63]
	v_mfma_f32_16x16x32_bf16 v[56:59], v[166:169], v[174:177], v[56:59]
	v_mfma_f32_16x16x32_bf16 v[52:55], v[146:149], v[182:185], v[52:55]
	v_mfma_f32_16x16x32_bf16 v[48:51], v[166:169], v[182:185], v[48:51]
	v_mfma_f32_16x16x32_bf16 v[44:47], v[146:149], v[194:197], v[44:47]
	v_mfma_f32_16x16x32_bf16 v[40:43], v[166:169], v[194:197], v[40:43]
	v_mfma_f32_16x16x32_bf16 v[36:39], v[146:149], v[202:205], v[36:39]
	v_mfma_f32_16x16x32_bf16 v[32:35], v[166:169], v[202:205], v[32:35]
	v_mfma_f32_16x16x32_bf16 v[60:63], v[162:165], v[178:181], v[60:63]
	v_mfma_f32_16x16x32_bf16 v[56:59], v[170:173], v[178:181], v[56:59]
	v_mfma_f32_16x16x32_bf16 v[52:55], v[162:165], v[190:193], v[52:55]
	v_mfma_f32_16x16x32_bf16 v[48:51], v[170:173], v[190:193], v[48:51]
	v_mfma_f32_16x16x32_bf16 v[44:47], v[162:165], v[198:201], v[44:47]
	v_mfma_f32_16x16x32_bf16 v[40:43], v[170:173], v[198:201], v[40:43]
	v_mfma_f32_16x16x32_bf16 v[36:39], v[162:165], v[206:209], v[36:39]
	v_mfma_f32_16x16x32_bf16 v[32:35], v[170:173], v[206:209], v[32:35]
	s_setprio 0
	s_barrier
	s_add_i32 s68, s75, s5
	v_lshl_add_u64 v[210:211], v[210:211], 0, s[16:17]
	s_mov_b32 m0, s68
	ds_read_b128 v[174:177], v225 offset:49152
	ds_read_b128 v[178:181], v225 offset:50176
	ds_read_b128 v[182:185], v225 offset:51200
	ds_read_b128 v[190:193], v225 offset:52224
	ds_read_b128 v[194:197], v225 offset:53248
	ds_read_b128 v[198:201], v225 offset:54272
	ds_read_b128 v[202:205], v225 offset:55296
	ds_read_b128 v[206:209], v225 offset:56320
	global_load_lds_dwordx4 v[210:211], off
	s_add_i32 m0, s68, 0x2000
	s_add_u32 s30, s30, 0x40080
	v_lshl_add_u64 v[210:211], v[212:213], 0, s[16:17]
	s_addc_u32 s31, s31, 0
	s_add_i32 s68, s83, s5
	global_load_lds_dwordx4 v[210:211], off
	v_lshl_add_u64 v[210:211], s[30:31], 0, v[152:153]
	s_mov_b32 m0, s68
	s_nop 0
	global_load_lds_dwordx4 v[210:211], off
	v_lshl_add_u64 v[210:211], s[30:31], 0, v[156:157]
	s_add_i32 m0, s68, 0x2000
	s_nop 0
	global_load_lds_dwordx4 v[210:211], off
	v_lshl_add_u64 v[210:211], v[214:215], 0, s[16:17]
	s_mov_b32 m0, s4
	s_nop 0
	global_load_lds_dwordx4 v[210:211], off
	v_lshl_add_u64 v[210:211], v[216:217], 0, s[16:17]
	s_mov_b32 m0, s90
	s_nop 0
	global_load_lds_dwordx4 v[210:211], off
	s_waitcnt vmcnt(8)
	s_waitcnt lgkmcnt(0)
	s_barrier
	s_setprio 1
	v_mfma_f32_16x16x32_bf16 v[94:97], v[98:101], v[174:177], v[94:97]
	v_mfma_f32_16x16x32_bf16 v[90:93], v[106:109], v[174:177], v[90:93]
	v_mfma_f32_16x16x32_bf16 v[86:89], v[98:101], v[182:185], v[86:89]
	v_mfma_f32_16x16x32_bf16 v[82:85], v[106:109], v[182:185], v[82:85]
	v_mfma_f32_16x16x32_bf16 v[78:81], v[98:101], v[194:197], v[78:81]
	v_mfma_f32_16x16x32_bf16 v[74:77], v[106:109], v[194:197], v[74:77]
	v_mfma_f32_16x16x32_bf16 v[70:73], v[98:101], v[202:205], v[70:73]
	v_mfma_f32_16x16x32_bf16 v[66:69], v[106:109], v[202:205], v[66:69]
	v_mfma_f32_16x16x32_bf16 v[94:97], v[102:105], v[178:181], v[94:97]
	v_mfma_f32_16x16x32_bf16 v[90:93], v[110:113], v[178:181], v[90:93]
	v_mfma_f32_16x16x32_bf16 v[86:89], v[102:105], v[190:193], v[86:89]
	v_mfma_f32_16x16x32_bf16 v[82:85], v[110:113], v[190:193], v[82:85]
	v_mfma_f32_16x16x32_bf16 v[78:81], v[102:105], v[198:201], v[78:81]
	v_mfma_f32_16x16x32_bf16 v[74:77], v[110:113], v[198:201], v[74:77]
	v_mfma_f32_16x16x32_bf16 v[70:73], v[102:105], v[206:209], v[70:73]
	v_mfma_f32_16x16x32_bf16 v[66:69], v[110:113], v[206:209], v[66:69]
	v_mfma_f32_16x16x32_bf16 v[28:31], v[146:149], v[174:177], v[28:31]
	v_mfma_f32_16x16x32_bf16 v[24:27], v[166:169], v[174:177], v[24:27]
	v_mfma_f32_16x16x32_bf16 v[20:23], v[146:149], v[182:185], v[20:23]
	v_mfma_f32_16x16x32_bf16 v[16:19], v[166:169], v[182:185], v[16:19]
	v_mfma_f32_16x16x32_bf16 v[12:15], v[146:149], v[194:197], v[12:15]
	v_mfma_f32_16x16x32_bf16 v[8:11], v[166:169], v[194:197], v[8:11]
	v_mfma_f32_16x16x32_bf16 v[4:7], v[146:149], v[202:205], v[4:7]
	v_mfma_f32_16x16x32_bf16 v[0:3], v[166:169], v[202:205], v[0:3]
	v_mfma_f32_16x16x32_bf16 v[28:31], v[162:165], v[178:181], v[28:31]
	v_mfma_f32_16x16x32_bf16 v[24:27], v[170:173], v[178:181], v[24:27]
	v_mfma_f32_16x16x32_bf16 v[20:23], v[162:165], v[190:193], v[20:23]
	v_mfma_f32_16x16x32_bf16 v[16:19], v[170:173], v[190:193], v[16:19]
	v_mfma_f32_16x16x32_bf16 v[12:15], v[162:165], v[198:201], v[12:15]
	v_mfma_f32_16x16x32_bf16 v[8:11], v[170:173], v[198:201], v[8:11]
	v_mfma_f32_16x16x32_bf16 v[4:7], v[162:165], v[206:209], v[4:7]
	v_mfma_f32_16x16x32_bf16 v[0:3], v[170:173], v[206:209], v[0:3]
	s_setprio 0
	s_add_i32 s74, s74, 2
	s_add_u32 s28, s28, 0x100
	s_addc_u32 s29, s29, 0
	s_add_u32 s72, s72, 0x100
	s_addc_u32 s73, s73, 0
	s_cmp_gt_u32 s74, 13
	s_barrier
	s_cbranch_scc0 .LBB0_1250
	s_and_b64 vcc, exec, s[44:45]
	s_cbranch_vccz .LBB0_1253
	s_barrier

.LBB0_1384:
	s_add_u32 s68, s30, 0xfffc0080
	s_addc_u32 s69, s31, -1
	s_add_i32 s77, 0, 0x10000
	s_cmp_eq_u32 s76, 12
	s_cselect_b32 s71, s49, s69
	s_cselect_b32 s70, s72, s68
	s_cselect_b32 s69, s45, s75
	s_cselect_b32 s68, s73, s74
	s_add_i32 s84, 0, 0x14000
	v_add_u32_e32 v126, s77, v162
	v_add_u32_e32 v165, s84, v162
	ds_read_b128 v[114:117], v126
	ds_read_b128 v[118:121], v126 offset:1024
	ds_read_b128 v[122:125], v126 offset:2048
	ds_read_b128 v[126:129], v126 offset:3072
	ds_read_b128 v[158:161], v165
	ds_read_b128 v[166:169], v165 offset:1024
	ds_read_b128 v[170:173], v165 offset:2048
	ds_read_b128 v[174:177], v165 offset:3072
	v_lshl_add_u64 v[214:215], s[30:31], 0, v[154:155]
	s_add_i32 m0, s11, 0xc000
	ds_read_b128 v[178:181], v164
	ds_read_b128 v[182:185], v164 offset:1024
	ds_read_b128 v[190:193], v164 offset:2048
	ds_read_b128 v[194:197], v164 offset:3072
	ds_read_b128 v[198:201], v164 offset:4096
	ds_read_b128 v[202:205], v164 offset:5120
	ds_read_b128 v[206:209], v164 offset:6144
	ds_read_b128 v[210:213], v164 offset:7168
	global_load_lds_dwordx4 v[214:215], off
	v_lshl_add_u64 v[214:215], s[30:31], 0, v[156:157]
	s_add_i32 m0, s11, 0xe000
	s_nop 0
	global_load_lds_dwordx4 v[214:215], off
	s_waitcnt vmcnt(8)
	s_waitcnt lgkmcnt(0)
	s_barrier
	s_setprio 1
	v_mfma_f32_16x16x32_bf16 v[142:145], v[114:117], v[178:181], v[142:145]
	v_mfma_f32_16x16x32_bf16 v[138:141], v[122:125], v[178:181], v[138:141]
	v_mfma_f32_16x16x32_bf16 v[110:113], v[114:117], v[190:193], v[110:113]
	v_mfma_f32_16x16x32_bf16 v[106:109], v[122:125], v[190:193], v[106:109]
	v_mfma_f32_16x16x32_bf16 v[94:97], v[114:117], v[198:201], v[94:97]
	v_mfma_f32_16x16x32_bf16 v[90:93], v[122:125], v[198:201], v[90:93]
	v_mfma_f32_16x16x32_bf16 v[78:81], v[114:117], v[206:209], v[78:81]
	v_mfma_f32_16x16x32_bf16 v[74:77], v[122:125], v[206:209], v[74:77]
	v_mfma_f32_16x16x32_bf16 v[142:145], v[118:121], v[182:185], v[142:145]
	v_mfma_f32_16x16x32_bf16 v[138:141], v[126:129], v[182:185], v[138:141]
	v_mfma_f32_16x16x32_bf16 v[110:113], v[118:121], v[194:197], v[110:113]
	v_mfma_f32_16x16x32_bf16 v[106:109], v[126:129], v[194:197], v[106:109]
	v_mfma_f32_16x16x32_bf16 v[94:97], v[118:121], v[202:205], v[94:97]
	v_mfma_f32_16x16x32_bf16 v[90:93], v[126:129], v[202:205], v[90:93]
	v_mfma_f32_16x16x32_bf16 v[78:81], v[118:121], v[210:213], v[78:81]
	v_mfma_f32_16x16x32_bf16 v[74:77], v[126:129], v[210:213], v[74:77]
	v_mfma_f32_16x16x32_bf16 v[134:137], v[158:161], v[178:181], v[134:137]
	v_mfma_f32_16x16x32_bf16 v[130:133], v[170:173], v[178:181], v[130:133]
	v_mfma_f32_16x16x32_bf16 v[102:105], v[158:161], v[190:193], v[102:105]
	v_mfma_f32_16x16x32_bf16 v[98:101], v[170:173], v[190:193], v[98:101]
	v_mfma_f32_16x16x32_bf16 v[86:89], v[158:161], v[198:201], v[86:89]
	v_mfma_f32_16x16x32_bf16 v[82:85], v[170:173], v[198:201], v[82:85]
	v_mfma_f32_16x16x32_bf16 v[70:73], v[158:161], v[206:209], v[70:73]
	v_mfma_f32_16x16x32_bf16 v[66:69], v[170:173], v[206:209], v[66:69]
	v_mfma_f32_16x16x32_bf16 v[134:137], v[166:169], v[182:185], v[134:137]
	v_mfma_f32_16x16x32_bf16 v[130:133], v[174:177], v[182:185], v[130:133]
	v_mfma_f32_16x16x32_bf16 v[102:105], v[166:169], v[194:197], v[102:105]
	v_mfma_f32_16x16x32_bf16 v[98:101], v[174:177], v[194:197], v[98:101]
	v_mfma_f32_16x16x32_bf16 v[86:89], v[166:169], v[202:205], v[86:89]
	v_mfma_f32_16x16x32_bf16 v[82:85], v[174:177], v[202:205], v[82:85]
	v_mfma_f32_16x16x32_bf16 v[70:73], v[166:169], v[210:213], v[70:73]
	v_mfma_f32_16x16x32_bf16 v[66:69], v[174:177], v[210:213], v[66:69]
	s_setprio 0
	s_barrier
	s_add_i32 s77, s77, s10
	v_lshl_add_u64 v[214:215], s[68:69], 0, v[148:149]
	s_mov_b32 m0, s77
	ds_read_b128 v[178:181], v164 offset:16384
	ds_read_b128 v[182:185], v164 offset:17408
	ds_read_b128 v[190:193], v164 offset:18432
	ds_read_b128 v[194:197], v164 offset:19456
	ds_read_b128 v[198:201], v164 offset:20480
	ds_read_b128 v[202:205], v164 offset:21504
	ds_read_b128 v[206:209], v164 offset:22528
	ds_read_b128 v[210:213], v164 offset:23552
	global_load_lds_dwordx4 v[214:215], off
	s_add_i32 m0, s77, 0x2000
	s_add_u32 s82, s68, 0x40000
	v_lshl_add_u64 v[216:217], s[68:69], 0, v[152:153]
	s_addc_u32 s83, s69, 0
	s_add_i32 s77, s84, s10
	global_load_lds_dwordx4 v[216:217], off
	v_lshl_add_u64 v[218:219], s[82:83], 0, v[148:149]
	s_mov_b32 m0, s77
	v_lshl_add_u64 v[220:221], s[70:71], 0, v[150:151]
	global_load_lds_dwordx4 v[218:219], off
	v_lshl_add_u64 v[218:219], s[82:83], 0, v[152:153]
	s_add_i32 m0, s77, 0x2000
	s_nop 0
	global_load_lds_dwordx4 v[218:219], off
	v_lshl_add_u64 v[218:219], s[70:71], 0, v[146:147]
	s_mov_b32 m0, s11
	s_nop 0
	global_load_lds_dwordx4 v[218:219], off
	s_mov_b32 m0, s13
	s_nop 0
	global_load_lds_dwordx4 v[220:221], off
	s_waitcnt vmcnt(8)
	s_waitcnt lgkmcnt(0)
	s_barrier
	s_setprio 1
	v_mfma_f32_16x16x32_bf16 v[60:63], v[114:117], v[178:181], v[60:63]
	v_mfma_f32_16x16x32_bf16 v[56:59], v[122:125], v[178:181], v[56:59]
	v_mfma_f32_16x16x32_bf16 v[44:47], v[114:117], v[190:193], v[44:47]
	v_mfma_f32_16x16x32_bf16 v[40:43], v[122:125], v[190:193], v[40:43]
	v_mfma_f32_16x16x32_bf16 v[28:31], v[114:117], v[198:201], v[28:31]
	v_mfma_f32_16x16x32_bf16 v[24:27], v[122:125], v[198:201], v[24:27]
	v_mfma_f32_16x16x32_bf16 v[12:15], v[114:117], v[206:209], v[12:15]
	v_mfma_f32_16x16x32_bf16 v[8:11], v[122:125], v[206:209], v[8:11]
	v_mfma_f32_16x16x32_bf16 v[60:63], v[118:121], v[182:185], v[60:63]
	v_mfma_f32_16x16x32_bf16 v[56:59], v[126:129], v[182:185], v[56:59]
	v_mfma_f32_16x16x32_bf16 v[44:47], v[118:121], v[194:197], v[44:47]
	v_mfma_f32_16x16x32_bf16 v[40:43], v[126:129], v[194:197], v[40:43]
	v_mfma_f32_16x16x32_bf16 v[28:31], v[118:121], v[202:205], v[28:31]
	v_mfma_f32_16x16x32_bf16 v[24:27], v[126:129], v[202:205], v[24:27]
	v_mfma_f32_16x16x32_bf16 v[12:15], v[118:121], v[210:213], v[12:15]
	v_mfma_f32_16x16x32_bf16 v[8:11], v[126:129], v[210:213], v[8:11]
	v_mfma_f32_16x16x32_bf16 v[52:55], v[158:161], v[178:181], v[52:55]
	v_mfma_f32_16x16x32_bf16 v[48:51], v[170:173], v[178:181], v[48:51]
	v_mfma_f32_16x16x32_bf16 v[36:39], v[158:161], v[190:193], v[36:39]
	v_mfma_f32_16x16x32_bf16 v[32:35], v[170:173], v[190:193], v[32:35]
	v_mfma_f32_16x16x32_bf16 v[20:23], v[158:161], v[198:201], v[20:23]
	v_mfma_f32_16x16x32_bf16 v[16:19], v[170:173], v[198:201], v[16:19]
	v_mfma_f32_16x16x32_bf16 v[4:7], v[158:161], v[206:209], v[4:7]
	v_mfma_f32_16x16x32_bf16 v[0:3], v[170:173], v[206:209], v[0:3]
	v_mfma_f32_16x16x32_bf16 v[52:55], v[166:169], v[182:185], v[52:55]
	v_mfma_f32_16x16x32_bf16 v[48:51], v[174:177], v[182:185], v[48:51]
	v_mfma_f32_16x16x32_bf16 v[36:39], v[166:169], v[194:197], v[36:39]
	v_mfma_f32_16x16x32_bf16 v[32:35], v[174:177], v[194:197], v[32:35]
	v_mfma_f32_16x16x32_bf16 v[20:23], v[166:169], v[202:205], v[20:23]
	v_mfma_f32_16x16x32_bf16 v[16:19], v[174:177], v[202:205], v[16:19]
	v_mfma_f32_16x16x32_bf16 v[4:7], v[166:169], v[210:213], v[4:7]
	v_mfma_f32_16x16x32_bf16 v[0:3], v[174:177], v[210:213], v[0:3]
	s_setprio 0
	s_barrier
	s_add_i32 s77, 0, 0x18000
	s_add_i32 s82, 0, 0x1c000
	v_add_u32_e32 v126, s77, v162
	v_add_u32_e32 v165, s82, v162
	ds_read_b128 v[114:117], v126
	ds_read_b128 v[118:121], v126 offset:1024
	ds_read_b128 v[122:125], v126 offset:2048
	ds_read_b128 v[126:129], v126 offset:3072
	ds_read_b128 v[158:161], v165
	ds_read_b128 v[166:169], v165 offset:1024
	ds_read_b128 v[170:173], v165 offset:2048
	ds_read_b128 v[174:177], v165 offset:3072
	s_add_u32 s70, s70, 0x40000
	s_addc_u32 s71, s71, 0
	s_mov_b32 m0, s19
	v_lshl_add_u64 v[222:223], s[70:71], 0, v[146:147]
	ds_read_b128 v[178:181], v164 offset:32768
	ds_read_b128 v[182:185], v164 offset:33792
	ds_read_b128 v[190:193], v164 offset:34816
	ds_read_b128 v[194:197], v164 offset:35840
	ds_read_b128 v[198:201], v164 offset:36864
	ds_read_b128 v[202:205], v164 offset:37888
	ds_read_b128 v[206:209], v164 offset:38912
	ds_read_b128 v[210:213], v164 offset:39936
	global_load_lds_dwordx4 v[222:223], off
	v_lshl_add_u64 v[222:223], s[70:71], 0, v[150:151]
	s_mov_b32 m0, s34
	s_nop 0
	global_load_lds_dwordx4 v[222:223], off
	s_waitcnt vmcnt(8)
	s_waitcnt lgkmcnt(0)
	s_barrier
	s_setprio 1
	v_mfma_f32_16x16x32_bf16 v[142:145], v[114:117], v[178:181], v[142:145]
	v_mfma_f32_16x16x32_bf16 v[138:141], v[122:125], v[178:181], v[138:141]
	v_mfma_f32_16x16x32_bf16 v[110:113], v[114:117], v[190:193], v[110:113]
	v_mfma_f32_16x16x32_bf16 v[106:109], v[122:125], v[190:193], v[106:109]
	v_mfma_f32_16x16x32_bf16 v[94:97], v[114:117], v[198:201], v[94:97]
	v_mfma_f32_16x16x32_bf16 v[90:93], v[122:125], v[198:201], v[90:93]
	v_mfma_f32_16x16x32_bf16 v[78:81], v[114:117], v[206:209], v[78:81]
	v_mfma_f32_16x16x32_bf16 v[74:77], v[122:125], v[206:209], v[74:77]
	v_mfma_f32_16x16x32_bf16 v[142:145], v[118:121], v[182:185], v[142:145]
	v_mfma_f32_16x16x32_bf16 v[138:141], v[126:129], v[182:185], v[138:141]
	v_mfma_f32_16x16x32_bf16 v[110:113], v[118:121], v[194:197], v[110:113]
	v_mfma_f32_16x16x32_bf16 v[106:109], v[126:129], v[194:197], v[106:109]
	v_mfma_f32_16x16x32_bf16 v[94:97], v[118:121], v[202:205], v[94:97]
	v_mfma_f32_16x16x32_bf16 v[90:93], v[126:129], v[202:205], v[90:93]
	v_mfma_f32_16x16x32_bf16 v[78:81], v[118:121], v[210:213], v[78:81]
	v_mfma_f32_16x16x32_bf16 v[74:77], v[126:129], v[210:213], v[74:77]
	v_mfma_f32_16x16x32_bf16 v[134:137], v[158:161], v[178:181], v[134:137]
	v_mfma_f32_16x16x32_bf16 v[130:133], v[170:173], v[178:181], v[130:133]
	v_mfma_f32_16x16x32_bf16 v[102:105], v[158:161], v[190:193], v[102:105]
	v_mfma_f32_16x16x32_bf16 v[98:101], v[170:173], v[190:193], v[98:101]
	v_mfma_f32_16x16x32_bf16 v[86:89], v[158:161], v[198:201], v[86:89]
	v_mfma_f32_16x16x32_bf16 v[82:85], v[170:173], v[198:201], v[82:85]
	v_mfma_f32_16x16x32_bf16 v[70:73], v[158:161], v[206:209], v[70:73]
	v_mfma_f32_16x16x32_bf16 v[66:69], v[170:173], v[206:209], v[66:69]
	v_mfma_f32_16x16x32_bf16 v[134:137], v[166:169], v[182:185], v[134:137]
	v_mfma_f32_16x16x32_bf16 v[130:133], v[174:177], v[182:185], v[130:133]
	v_mfma_f32_16x16x32_bf16 v[102:105], v[166:169], v[194:197], v[102:105]
	v_mfma_f32_16x16x32_bf16 v[98:101], v[174:177], v[194:197], v[98:101]
	v_mfma_f32_16x16x32_bf16 v[86:89], v[166:169], v[202:205], v[86:89]
	v_mfma_f32_16x16x32_bf16 v[82:85], v[174:177], v[202:205], v[82:85]
	v_mfma_f32_16x16x32_bf16 v[70:73], v[166:169], v[210:213], v[70:73]
	v_mfma_f32_16x16x32_bf16 v[66:69], v[174:177], v[210:213], v[66:69]
	s_setprio 0
	s_barrier
	s_add_i32 s70, s77, s10
	v_lshl_add_u64 v[214:215], v[214:215], 0, s[16:17]
	s_mov_b32 m0, s70
	ds_read_b128 v[178:181], v164 offset:49152
	ds_read_b128 v[182:185], v164 offset:50176
	ds_read_b128 v[190:193], v164 offset:51200
	ds_read_b128 v[194:197], v164 offset:52224
	ds_read_b128 v[198:201], v164 offset:53248
	ds_read_b128 v[202:205], v164 offset:54272
	ds_read_b128 v[206:209], v164 offset:55296
	ds_read_b128 v[210:213], v164 offset:56320
	global_load_lds_dwordx4 v[214:215], off
	s_add_i32 m0, s70, 0x2000
	s_add_u32 s68, s68, 0x40080
	v_lshl_add_u64 v[214:215], v[216:217], 0, s[16:17]
	s_addc_u32 s69, s69, 0
	s_add_i32 s70, s82, s10
	global_load_lds_dwordx4 v[214:215], off
	v_lshl_add_u64 v[214:215], s[68:69], 0, v[148:149]
	s_mov_b32 m0, s70
	s_nop 0
	global_load_lds_dwordx4 v[214:215], off
	v_lshl_add_u64 v[214:215], s[68:69], 0, v[152:153]
	s_add_i32 m0, s70, 0x2000
	s_nop 0
	global_load_lds_dwordx4 v[214:215], off
	v_lshl_add_u64 v[214:215], v[218:219], 0, s[16:17]
	s_mov_b32 m0, s47
	s_nop 0
	global_load_lds_dwordx4 v[214:215], off
	v_lshl_add_u64 v[214:215], v[220:221], 0, s[16:17]
	s_mov_b32 m0, s61
	s_nop 0
	global_load_lds_dwordx4 v[214:215], off
	s_waitcnt vmcnt(8)
	s_waitcnt lgkmcnt(0)
	s_barrier
	s_setprio 1
	v_mfma_f32_16x16x32_bf16 v[60:63], v[114:117], v[178:181], v[60:63]
	v_mfma_f32_16x16x32_bf16 v[56:59], v[122:125], v[178:181], v[56:59]
	v_mfma_f32_16x16x32_bf16 v[44:47], v[114:117], v[190:193], v[44:47]
	v_mfma_f32_16x16x32_bf16 v[40:43], v[122:125], v[190:193], v[40:43]
	v_mfma_f32_16x16x32_bf16 v[28:31], v[114:117], v[198:201], v[28:31]
	v_mfma_f32_16x16x32_bf16 v[24:27], v[122:125], v[198:201], v[24:27]
	v_mfma_f32_16x16x32_bf16 v[12:15], v[114:117], v[206:209], v[12:15]
	v_mfma_f32_16x16x32_bf16 v[8:11], v[122:125], v[206:209], v[8:11]
	v_mfma_f32_16x16x32_bf16 v[60:63], v[118:121], v[182:185], v[60:63]
	v_mfma_f32_16x16x32_bf16 v[56:59], v[126:129], v[182:185], v[56:59]
	v_mfma_f32_16x16x32_bf16 v[44:47], v[118:121], v[194:197], v[44:47]
	v_mfma_f32_16x16x32_bf16 v[40:43], v[126:129], v[194:197], v[40:43]
	v_mfma_f32_16x16x32_bf16 v[28:31], v[118:121], v[202:205], v[28:31]
	v_mfma_f32_16x16x32_bf16 v[24:27], v[126:129], v[202:205], v[24:27]
	v_mfma_f32_16x16x32_bf16 v[12:15], v[118:121], v[210:213], v[12:15]
	v_mfma_f32_16x16x32_bf16 v[8:11], v[126:129], v[210:213], v[8:11]
	v_mfma_f32_16x16x32_bf16 v[52:55], v[158:161], v[178:181], v[52:55]
	v_mfma_f32_16x16x32_bf16 v[48:51], v[170:173], v[178:181], v[48:51]
	v_mfma_f32_16x16x32_bf16 v[36:39], v[158:161], v[190:193], v[36:39]
	v_mfma_f32_16x16x32_bf16 v[32:35], v[170:173], v[190:193], v[32:35]
	v_mfma_f32_16x16x32_bf16 v[20:23], v[158:161], v[198:201], v[20:23]
	v_mfma_f32_16x16x32_bf16 v[16:19], v[170:173], v[198:201], v[16:19]
	v_mfma_f32_16x16x32_bf16 v[4:7], v[158:161], v[206:209], v[4:7]
	v_mfma_f32_16x16x32_bf16 v[0:3], v[170:173], v[206:209], v[0:3]
	v_mfma_f32_16x16x32_bf16 v[52:55], v[166:169], v[182:185], v[52:55]
	v_mfma_f32_16x16x32_bf16 v[48:51], v[174:177], v[182:185], v[48:51]
	v_mfma_f32_16x16x32_bf16 v[36:39], v[166:169], v[194:197], v[36:39]
	v_mfma_f32_16x16x32_bf16 v[32:35], v[174:177], v[194:197], v[32:35]
	v_mfma_f32_16x16x32_bf16 v[20:23], v[166:169], v[202:205], v[20:23]
	v_mfma_f32_16x16x32_bf16 v[16:19], v[174:177], v[202:205], v[16:19]
	v_mfma_f32_16x16x32_bf16 v[4:7], v[166:169], v[210:213], v[4:7]
	v_mfma_f32_16x16x32_bf16 v[0:3], v[174:177], v[210:213], v[0:3]
	s_setprio 0
	s_add_i32 s76, s76, 2
	s_add_u32 s30, s30, 0x100
	s_addc_u32 s31, s31, 0
	s_add_u32 s74, s74, 0x100
	s_addc_u32 s75, s75, 0
	s_cmp_gt_u32 s76, 13
	s_barrier
	s_cbranch_scc0 .LBB0_1384
	s_and_b64 vcc, exec, s[42:43]
	s_cbranch_vccz .LBB0_1387
	s_barrier

.LBB0_1461:
	s_add_u32 s30, s28, 0xfff00080
	s_addc_u32 s31, s29, -1
	s_add_i32 s84, 0, 0x10000
	s_cmp_eq_u32 s91, 60
	s_cselect_b32 s49, s35, s31
	s_cselect_b32 s48, s47, s30
	s_cselect_b32 s31, s69, s83
	s_cselect_b32 s30, s71, s82
	s_add_i32 s92, 0, 0x14000
	v_add_u32_e32 v138, s84, v246
	v_add_u32_e32 v158, s92, v246
	ds_read_b128 v[114:117], v138
	ds_read_b128 v[118:121], v138 offset:1024
	ds_read_b128 v[130:133], v138 offset:2048
	ds_read_b128 v[138:141], v138 offset:3072
	ds_read_b128 v[146:149], v158
	ds_read_b128 v[150:153], v158 offset:1024
	ds_read_b128 v[154:157], v158 offset:2048
	ds_read_b128 v[158:161], v158 offset:3072
	v_lshl_add_u64 v[210:211], s[28:29], 0, v[198:199]
	s_add_i32 m0, s11, 0xc000
	ds_read_b128 v[162:165], v251
	ds_read_b128 v[166:169], v251 offset:1024
	ds_read_b128 v[170:173], v251 offset:2048
	ds_read_b128 v[174:177], v251 offset:3072
	ds_read_b128 v[178:181], v251 offset:4096
	ds_read_b128 v[182:185], v251 offset:5120
	ds_read_b128 v[202:205], v251 offset:6144
	ds_read_b128 v[206:209], v251 offset:7168
	global_load_lds_dwordx4 v[210:211], off
	v_lshl_add_u64 v[210:211], s[28:29], 0, v[200:201]
	s_add_i32 m0, s11, 0xe000
	s_nop 0
	global_load_lds_dwordx4 v[210:211], off
	s_waitcnt vmcnt(8)
	s_waitcnt lgkmcnt(0)
	s_barrier
	s_setprio 1
	v_mfma_f32_16x16x32_bf16 v[126:129], v[114:117], v[162:165], v[126:129]
	v_mfma_f32_16x16x32_bf16 v[122:125], v[130:133], v[162:165], v[122:125]
	v_mfma_f32_16x16x32_bf16 v[110:113], v[114:117], v[170:173], v[110:113]
	v_mfma_f32_16x16x32_bf16 v[106:109], v[130:133], v[170:173], v[106:109]
	v_mfma_f32_16x16x32_bf16 v[94:97], v[114:117], v[178:181], v[94:97]
	v_mfma_f32_16x16x32_bf16 v[90:93], v[130:133], v[178:181], v[90:93]
	v_mfma_f32_16x16x32_bf16 v[78:81], v[114:117], v[202:205], v[78:81]
	v_mfma_f32_16x16x32_bf16 v[74:77], v[130:133], v[202:205], v[74:77]
	v_mfma_f32_16x16x32_bf16 v[126:129], v[118:121], v[166:169], v[126:129]
	v_mfma_f32_16x16x32_bf16 v[122:125], v[138:141], v[166:169], v[122:125]
	v_mfma_f32_16x16x32_bf16 v[110:113], v[118:121], v[174:177], v[110:113]
	v_mfma_f32_16x16x32_bf16 v[106:109], v[138:141], v[174:177], v[106:109]
	v_mfma_f32_16x16x32_bf16 v[94:97], v[118:121], v[182:185], v[94:97]
	v_mfma_f32_16x16x32_bf16 v[90:93], v[138:141], v[182:185], v[90:93]
	v_mfma_f32_16x16x32_bf16 v[78:81], v[118:121], v[206:209], v[78:81]
	v_mfma_f32_16x16x32_bf16 v[74:77], v[138:141], v[206:209], v[74:77]
	v_mfma_f32_16x16x32_bf16 v[142:145], v[146:149], v[162:165], v[142:145]
	v_mfma_f32_16x16x32_bf16 v[134:137], v[154:157], v[162:165], v[134:137]
	v_mfma_f32_16x16x32_bf16 v[102:105], v[146:149], v[170:173], v[102:105]
	v_mfma_f32_16x16x32_bf16 v[98:101], v[154:157], v[170:173], v[98:101]
	v_mfma_f32_16x16x32_bf16 v[86:89], v[146:149], v[178:181], v[86:89]
	v_mfma_f32_16x16x32_bf16 v[82:85], v[154:157], v[178:181], v[82:85]
	v_mfma_f32_16x16x32_bf16 v[70:73], v[146:149], v[202:205], v[70:73]
	v_mfma_f32_16x16x32_bf16 v[66:69], v[154:157], v[202:205], v[66:69]
	v_mfma_f32_16x16x32_bf16 v[142:145], v[150:153], v[166:169], v[142:145]
	v_mfma_f32_16x16x32_bf16 v[134:137], v[158:161], v[166:169], v[134:137]
	v_mfma_f32_16x16x32_bf16 v[102:105], v[150:153], v[174:177], v[102:105]
	v_mfma_f32_16x16x32_bf16 v[98:101], v[158:161], v[174:177], v[98:101]
	v_mfma_f32_16x16x32_bf16 v[86:89], v[150:153], v[182:185], v[86:89]
	v_mfma_f32_16x16x32_bf16 v[82:85], v[158:161], v[182:185], v[82:85]
	v_mfma_f32_16x16x32_bf16 v[70:73], v[150:153], v[206:209], v[70:73]
	v_mfma_f32_16x16x32_bf16 v[66:69], v[158:161], v[206:209], v[66:69]
	s_setprio 0
	s_barrier
	s_add_i32 s84, s84, s10
	v_lshl_add_u64 v[210:211], s[30:31], 0, v[192:193]
	s_mov_b32 m0, s84
	ds_read_b128 v[162:165], v251 offset:16384
	ds_read_b128 v[166:169], v251 offset:17408
	ds_read_b128 v[170:173], v251 offset:18432
	ds_read_b128 v[174:177], v251 offset:19456
	ds_read_b128 v[178:181], v251 offset:20480
	ds_read_b128 v[182:185], v251 offset:21504
	ds_read_b128 v[202:205], v251 offset:22528
	ds_read_b128 v[206:209], v251 offset:23552
	global_load_lds_dwordx4 v[210:211], off
	s_add_i32 m0, s84, 0x2000
	s_add_u32 s84, s30, 0x100000
	v_lshl_add_u64 v[212:213], s[30:31], 0, v[196:197]
	s_addc_u32 s85, s31, 0
	s_add_i32 s92, s92, s10
	global_load_lds_dwordx4 v[212:213], off
	v_lshl_add_u64 v[214:215], s[84:85], 0, v[192:193]
	s_mov_b32 m0, s92
	v_lshl_add_u64 v[216:217], s[48:49], 0, v[194:195]
	global_load_lds_dwordx4 v[214:215], off
	v_lshl_add_u64 v[214:215], s[84:85], 0, v[196:197]
	s_add_i32 m0, s92, 0x2000
	s_nop 0
	global_load_lds_dwordx4 v[214:215], off
	v_lshl_add_u64 v[214:215], s[48:49], 0, v[190:191]
	s_mov_b32 m0, s11
	s_nop 0
	global_load_lds_dwordx4 v[214:215], off
	s_mov_b32 m0, s13
	s_nop 0
	global_load_lds_dwordx4 v[216:217], off
	s_waitcnt vmcnt(8)
	s_waitcnt lgkmcnt(0)
	s_barrier
	s_setprio 1
	v_mfma_f32_16x16x32_bf16 v[60:63], v[114:117], v[162:165], v[60:63]
	v_mfma_f32_16x16x32_bf16 v[56:59], v[130:133], v[162:165], v[56:59]
	v_mfma_f32_16x16x32_bf16 v[44:47], v[114:117], v[170:173], v[44:47]
	v_mfma_f32_16x16x32_bf16 v[40:43], v[130:133], v[170:173], v[40:43]
	v_mfma_f32_16x16x32_bf16 v[28:31], v[114:117], v[178:181], v[28:31]
	v_mfma_f32_16x16x32_bf16 v[24:27], v[130:133], v[178:181], v[24:27]
	v_mfma_f32_16x16x32_bf16 v[12:15], v[114:117], v[202:205], v[12:15]
	v_mfma_f32_16x16x32_bf16 v[8:11], v[130:133], v[202:205], v[8:11]
	v_mfma_f32_16x16x32_bf16 v[60:63], v[118:121], v[166:169], v[60:63]
	v_mfma_f32_16x16x32_bf16 v[56:59], v[138:141], v[166:169], v[56:59]
	v_mfma_f32_16x16x32_bf16 v[44:47], v[118:121], v[174:177], v[44:47]
	v_mfma_f32_16x16x32_bf16 v[40:43], v[138:141], v[174:177], v[40:43]
	v_mfma_f32_16x16x32_bf16 v[28:31], v[118:121], v[182:185], v[28:31]
	v_mfma_f32_16x16x32_bf16 v[24:27], v[138:141], v[182:185], v[24:27]
	v_mfma_f32_16x16x32_bf16 v[12:15], v[118:121], v[206:209], v[12:15]
	v_mfma_f32_16x16x32_bf16 v[8:11], v[138:141], v[206:209], v[8:11]
	v_mfma_f32_16x16x32_bf16 v[52:55], v[146:149], v[162:165], v[52:55]
	v_mfma_f32_16x16x32_bf16 v[48:51], v[154:157], v[162:165], v[48:51]
	v_mfma_f32_16x16x32_bf16 v[36:39], v[146:149], v[170:173], v[36:39]
	v_mfma_f32_16x16x32_bf16 v[32:35], v[154:157], v[170:173], v[32:35]
	v_mfma_f32_16x16x32_bf16 v[20:23], v[146:149], v[178:181], v[20:23]
	v_mfma_f32_16x16x32_bf16 v[16:19], v[154:157], v[178:181], v[16:19]
	v_mfma_f32_16x16x32_bf16 v[4:7], v[146:149], v[202:205], v[4:7]
	v_mfma_f32_16x16x32_bf16 v[0:3], v[154:157], v[202:205], v[0:3]
	v_mfma_f32_16x16x32_bf16 v[52:55], v[150:153], v[166:169], v[52:55]
	v_mfma_f32_16x16x32_bf16 v[48:51], v[158:161], v[166:169], v[48:51]
	v_mfma_f32_16x16x32_bf16 v[36:39], v[150:153], v[174:177], v[36:39]
	v_mfma_f32_16x16x32_bf16 v[32:35], v[158:161], v[174:177], v[32:35]
	v_mfma_f32_16x16x32_bf16 v[20:23], v[150:153], v[182:185], v[20:23]
	v_mfma_f32_16x16x32_bf16 v[16:19], v[158:161], v[182:185], v[16:19]
	v_mfma_f32_16x16x32_bf16 v[4:7], v[150:153], v[206:209], v[4:7]
	v_mfma_f32_16x16x32_bf16 v[0:3], v[158:161], v[206:209], v[0:3]
	s_setprio 0
	s_barrier
	s_add_i32 s84, 0, 0x18000
	s_add_i32 s85, 0, 0x1c000
	v_add_u32_e32 v138, s84, v246
	v_add_u32_e32 v158, s85, v246
	ds_read_b128 v[114:117], v138
	ds_read_b128 v[118:121], v138 offset:1024
	ds_read_b128 v[130:133], v138 offset:2048
	ds_read_b128 v[138:141], v138 offset:3072
	ds_read_b128 v[146:149], v158
	ds_read_b128 v[150:153], v158 offset:1024
	ds_read_b128 v[154:157], v158 offset:2048
	ds_read_b128 v[158:161], v158 offset:3072
	s_add_u32 s48, s48, 0x100000
	s_addc_u32 s49, s49, 0
	s_mov_b32 m0, s19
	v_lshl_add_u64 v[218:219], s[48:49], 0, v[190:191]
	ds_read_b128 v[162:165], v251 offset:32768
	ds_read_b128 v[166:169], v251 offset:33792
	ds_read_b128 v[170:173], v251 offset:34816
	ds_read_b128 v[174:177], v251 offset:35840
	ds_read_b128 v[178:181], v251 offset:36864
	ds_read_b128 v[182:185], v251 offset:37888
	ds_read_b128 v[202:205], v251 offset:38912
	ds_read_b128 v[206:209], v251 offset:39936
	global_load_lds_dwordx4 v[218:219], off
	v_lshl_add_u64 v[218:219], s[48:49], 0, v[194:195]
	s_mov_b32 m0, s61
	s_nop 0
	global_load_lds_dwordx4 v[218:219], off
	s_waitcnt vmcnt(8)
	s_waitcnt lgkmcnt(0)
	s_barrier
	s_setprio 1
	v_mfma_f32_16x16x32_bf16 v[126:129], v[114:117], v[162:165], v[126:129]
	v_mfma_f32_16x16x32_bf16 v[122:125], v[130:133], v[162:165], v[122:125]
	v_mfma_f32_16x16x32_bf16 v[110:113], v[114:117], v[170:173], v[110:113]
	v_mfma_f32_16x16x32_bf16 v[106:109], v[130:133], v[170:173], v[106:109]
	v_mfma_f32_16x16x32_bf16 v[94:97], v[114:117], v[178:181], v[94:97]
	v_mfma_f32_16x16x32_bf16 v[90:93], v[130:133], v[178:181], v[90:93]
	v_mfma_f32_16x16x32_bf16 v[78:81], v[114:117], v[202:205], v[78:81]
	v_mfma_f32_16x16x32_bf16 v[74:77], v[130:133], v[202:205], v[74:77]
	v_mfma_f32_16x16x32_bf16 v[126:129], v[118:121], v[166:169], v[126:129]
	v_mfma_f32_16x16x32_bf16 v[122:125], v[138:141], v[166:169], v[122:125]
	v_mfma_f32_16x16x32_bf16 v[110:113], v[118:121], v[174:177], v[110:113]
	v_mfma_f32_16x16x32_bf16 v[106:109], v[138:141], v[174:177], v[106:109]
	v_mfma_f32_16x16x32_bf16 v[94:97], v[118:121], v[182:185], v[94:97]
	v_mfma_f32_16x16x32_bf16 v[90:93], v[138:141], v[182:185], v[90:93]
	v_mfma_f32_16x16x32_bf16 v[78:81], v[118:121], v[206:209], v[78:81]
	v_mfma_f32_16x16x32_bf16 v[74:77], v[138:141], v[206:209], v[74:77]
	v_mfma_f32_16x16x32_bf16 v[142:145], v[146:149], v[162:165], v[142:145]
	v_mfma_f32_16x16x32_bf16 v[134:137], v[154:157], v[162:165], v[134:137]
	v_mfma_f32_16x16x32_bf16 v[102:105], v[146:149], v[170:173], v[102:105]
	v_mfma_f32_16x16x32_bf16 v[98:101], v[154:157], v[170:173], v[98:101]
	v_mfma_f32_16x16x32_bf16 v[86:89], v[146:149], v[178:181], v[86:89]
	v_mfma_f32_16x16x32_bf16 v[82:85], v[154:157], v[178:181], v[82:85]
	v_mfma_f32_16x16x32_bf16 v[70:73], v[146:149], v[202:205], v[70:73]
	v_mfma_f32_16x16x32_bf16 v[66:69], v[154:157], v[202:205], v[66:69]
	v_mfma_f32_16x16x32_bf16 v[142:145], v[150:153], v[166:169], v[142:145]
	v_mfma_f32_16x16x32_bf16 v[134:137], v[158:161], v[166:169], v[134:137]
	v_mfma_f32_16x16x32_bf16 v[102:105], v[150:153], v[174:177], v[102:105]
	v_mfma_f32_16x16x32_bf16 v[98:101], v[158:161], v[174:177], v[98:101]
	v_mfma_f32_16x16x32_bf16 v[86:89], v[150:153], v[182:185], v[86:89]
	v_mfma_f32_16x16x32_bf16 v[82:85], v[158:161], v[182:185], v[82:85]
	v_mfma_f32_16x16x32_bf16 v[70:73], v[150:153], v[206:209], v[70:73]
	v_mfma_f32_16x16x32_bf16 v[66:69], v[158:161], v[206:209], v[66:69]
	s_setprio 0
	s_barrier
	s_add_i32 s48, s84, s10
	v_lshl_add_u64 v[210:211], v[210:211], 0, s[16:17]
	s_mov_b32 m0, s48
	ds_read_b128 v[162:165], v251 offset:49152
	ds_read_b128 v[166:169], v251 offset:50176
	ds_read_b128 v[170:173], v251 offset:51200
	ds_read_b128 v[174:177], v251 offset:52224
	ds_read_b128 v[178:181], v251 offset:53248
	ds_read_b128 v[182:185], v251 offset:54272
	ds_read_b128 v[202:205], v251 offset:55296
	ds_read_b128 v[206:209], v251 offset:56320
	global_load_lds_dwordx4 v[210:211], off
	s_add_i32 m0, s48, 0x2000
	s_add_u32 s30, s30, 0x100080
	v_lshl_add_u64 v[210:211], v[212:213], 0, s[16:17]
	s_addc_u32 s31, s31, 0
	s_add_i32 s48, s85, s10
	global_load_lds_dwordx4 v[210:211], off
	v_lshl_add_u64 v[210:211], s[30:31], 0, v[192:193]
	s_mov_b32 m0, s48
	s_nop 0
	global_load_lds_dwordx4 v[210:211], off
	v_lshl_add_u64 v[210:211], s[30:31], 0, v[196:197]
	s_add_i32 m0, s48, 0x2000
	s_nop 0
	global_load_lds_dwordx4 v[210:211], off
	v_lshl_add_u64 v[210:211], v[214:215], 0, s[16:17]
	s_mov_b32 m0, s76
	s_nop 0
	global_load_lds_dwordx4 v[210:211], off
	v_lshl_add_u64 v[210:211], v[216:217], 0, s[16:17]
	s_mov_b32 m0, s77
	s_nop 0
	global_load_lds_dwordx4 v[210:211], off
	s_waitcnt vmcnt(8)
	s_waitcnt lgkmcnt(0)
	s_barrier
	s_setprio 1
	v_mfma_f32_16x16x32_bf16 v[60:63], v[114:117], v[162:165], v[60:63]
	v_mfma_f32_16x16x32_bf16 v[56:59], v[130:133], v[162:165], v[56:59]
	v_mfma_f32_16x16x32_bf16 v[44:47], v[114:117], v[170:173], v[44:47]
	v_mfma_f32_16x16x32_bf16 v[40:43], v[130:133], v[170:173], v[40:43]
	v_mfma_f32_16x16x32_bf16 v[28:31], v[114:117], v[178:181], v[28:31]
	v_mfma_f32_16x16x32_bf16 v[24:27], v[130:133], v[178:181], v[24:27]
	v_mfma_f32_16x16x32_bf16 v[12:15], v[114:117], v[202:205], v[12:15]
	v_mfma_f32_16x16x32_bf16 v[8:11], v[130:133], v[202:205], v[8:11]
	v_mfma_f32_16x16x32_bf16 v[60:63], v[118:121], v[166:169], v[60:63]
	v_mfma_f32_16x16x32_bf16 v[56:59], v[138:141], v[166:169], v[56:59]
	v_mfma_f32_16x16x32_bf16 v[44:47], v[118:121], v[174:177], v[44:47]
	v_mfma_f32_16x16x32_bf16 v[40:43], v[138:141], v[174:177], v[40:43]
	v_mfma_f32_16x16x32_bf16 v[28:31], v[118:121], v[182:185], v[28:31]
	v_mfma_f32_16x16x32_bf16 v[24:27], v[138:141], v[182:185], v[24:27]
	v_mfma_f32_16x16x32_bf16 v[12:15], v[118:121], v[206:209], v[12:15]
	v_mfma_f32_16x16x32_bf16 v[8:11], v[138:141], v[206:209], v[8:11]
	v_mfma_f32_16x16x32_bf16 v[52:55], v[146:149], v[162:165], v[52:55]
	v_mfma_f32_16x16x32_bf16 v[48:51], v[154:157], v[162:165], v[48:51]
	v_mfma_f32_16x16x32_bf16 v[36:39], v[146:149], v[170:173], v[36:39]
	v_mfma_f32_16x16x32_bf16 v[32:35], v[154:157], v[170:173], v[32:35]
	v_mfma_f32_16x16x32_bf16 v[20:23], v[146:149], v[178:181], v[20:23]
	v_mfma_f32_16x16x32_bf16 v[16:19], v[154:157], v[178:181], v[16:19]
	v_mfma_f32_16x16x32_bf16 v[4:7], v[146:149], v[202:205], v[4:7]
	v_mfma_f32_16x16x32_bf16 v[0:3], v[154:157], v[202:205], v[0:3]
	v_mfma_f32_16x16x32_bf16 v[52:55], v[150:153], v[166:169], v[52:55]
	v_mfma_f32_16x16x32_bf16 v[48:51], v[158:161], v[166:169], v[48:51]
	v_mfma_f32_16x16x32_bf16 v[36:39], v[150:153], v[174:177], v[36:39]
	v_mfma_f32_16x16x32_bf16 v[32:35], v[158:161], v[174:177], v[32:35]
	v_mfma_f32_16x16x32_bf16 v[20:23], v[150:153], v[182:185], v[20:23]
	v_mfma_f32_16x16x32_bf16 v[16:19], v[158:161], v[182:185], v[16:19]
	v_mfma_f32_16x16x32_bf16 v[4:7], v[150:153], v[206:209], v[4:7]
	v_mfma_f32_16x16x32_bf16 v[0:3], v[158:161], v[206:209], v[0:3]
	s_setprio 0
	s_add_i32 s91, s91, 2
	s_add_u32 s28, s28, 0x100
	s_addc_u32 s29, s29, 0
	s_add_u32 s82, s82, 0x100
	s_addc_u32 s83, s83, 0
	s_cmp_gt_u32 s91, 61
	s_barrier
	s_cbranch_scc0 .LBB0_1461
	s_and_b64 vcc, exec, s[64:65]
	s_cbranch_vccz .LBB0_1464
	s_barrier

.LBB0_1532:
	s_add_u32 s30, s28, 0xfff00080
	s_addc_u32 s31, s29, -1
	s_add_i32 s73, 0, 0x10000
	s_cmp_eq_u32 s72, 60
	s_cselect_b32 s67, s49, s31
	s_cselect_b32 s66, s68, s30
	s_cselect_b32 s31, s47, s71
	s_cselect_b32 s30, s69, s70
	s_add_i32 s75, 0, 0x14000
	v_add_u32_e32 v110, s73, v223
	v_add_u32_e32 v170, s75, v223
	ds_read_b128 v[98:101], v110
	ds_read_b128 v[102:105], v110 offset:1024
	ds_read_b128 v[106:109], v110 offset:2048
	ds_read_b128 v[110:113], v110 offset:3072
	ds_read_b128 v[146:149], v170
	ds_read_b128 v[162:165], v170 offset:1024
	ds_read_b128 v[166:169], v170 offset:2048
	ds_read_b128 v[170:173], v170 offset:3072
	v_lshl_add_u64 v[210:211], s[28:29], 0, v[158:159]
	s_add_i32 m0, s1, 0xc000
	ds_read_b128 v[174:177], v225
	ds_read_b128 v[178:181], v225 offset:1024
	ds_read_b128 v[182:185], v225 offset:2048
	ds_read_b128 v[190:193], v225 offset:3072
	ds_read_b128 v[194:197], v225 offset:4096
	ds_read_b128 v[198:201], v225 offset:5120
	ds_read_b128 v[202:205], v225 offset:6144
	ds_read_b128 v[206:209], v225 offset:7168
	global_load_lds_dwordx4 v[210:211], off
	v_lshl_add_u64 v[210:211], s[28:29], 0, v[160:161]
	s_add_i32 m0, s1, 0xe000
	s_nop 0
	global_load_lds_dwordx4 v[210:211], off
	s_waitcnt vmcnt(8)
	s_waitcnt lgkmcnt(0)
	s_barrier
	s_setprio 1
	v_mfma_f32_16x16x32_bf16 v[142:145], v[98:101], v[174:177], v[142:145]
	v_mfma_f32_16x16x32_bf16 v[138:141], v[106:109], v[174:177], v[138:141]
	v_mfma_f32_16x16x32_bf16 v[134:137], v[98:101], v[182:185], v[134:137]
	v_mfma_f32_16x16x32_bf16 v[130:133], v[106:109], v[182:185], v[130:133]
	v_mfma_f32_16x16x32_bf16 v[126:129], v[98:101], v[194:197], v[126:129]
	v_mfma_f32_16x16x32_bf16 v[122:125], v[106:109], v[194:197], v[122:125]
	v_mfma_f32_16x16x32_bf16 v[118:121], v[98:101], v[202:205], v[118:121]
	v_mfma_f32_16x16x32_bf16 v[114:117], v[106:109], v[202:205], v[114:117]
	v_mfma_f32_16x16x32_bf16 v[142:145], v[102:105], v[178:181], v[142:145]
	v_mfma_f32_16x16x32_bf16 v[138:141], v[110:113], v[178:181], v[138:141]
	v_mfma_f32_16x16x32_bf16 v[134:137], v[102:105], v[190:193], v[134:137]
	v_mfma_f32_16x16x32_bf16 v[130:133], v[110:113], v[190:193], v[130:133]
	v_mfma_f32_16x16x32_bf16 v[126:129], v[102:105], v[198:201], v[126:129]
	v_mfma_f32_16x16x32_bf16 v[122:125], v[110:113], v[198:201], v[122:125]
	v_mfma_f32_16x16x32_bf16 v[118:121], v[102:105], v[206:209], v[118:121]
	v_mfma_f32_16x16x32_bf16 v[114:117], v[110:113], v[206:209], v[114:117]
	v_mfma_f32_16x16x32_bf16 v[60:63], v[146:149], v[174:177], v[60:63]
	v_mfma_f32_16x16x32_bf16 v[56:59], v[166:169], v[174:177], v[56:59]
	v_mfma_f32_16x16x32_bf16 v[52:55], v[146:149], v[182:185], v[52:55]
	v_mfma_f32_16x16x32_bf16 v[48:51], v[166:169], v[182:185], v[48:51]
	v_mfma_f32_16x16x32_bf16 v[44:47], v[146:149], v[194:197], v[44:47]
	v_mfma_f32_16x16x32_bf16 v[40:43], v[166:169], v[194:197], v[40:43]
	v_mfma_f32_16x16x32_bf16 v[36:39], v[146:149], v[202:205], v[36:39]
	v_mfma_f32_16x16x32_bf16 v[32:35], v[166:169], v[202:205], v[32:35]
	v_mfma_f32_16x16x32_bf16 v[60:63], v[162:165], v[178:181], v[60:63]
	v_mfma_f32_16x16x32_bf16 v[56:59], v[170:173], v[178:181], v[56:59]
	v_mfma_f32_16x16x32_bf16 v[52:55], v[162:165], v[190:193], v[52:55]
	v_mfma_f32_16x16x32_bf16 v[48:51], v[170:173], v[190:193], v[48:51]
	v_mfma_f32_16x16x32_bf16 v[44:47], v[162:165], v[198:201], v[44:47]
	v_mfma_f32_16x16x32_bf16 v[40:43], v[170:173], v[198:201], v[40:43]
	v_mfma_f32_16x16x32_bf16 v[36:39], v[162:165], v[206:209], v[36:39]
	v_mfma_f32_16x16x32_bf16 v[32:35], v[170:173], v[206:209], v[32:35]
	s_setprio 0
	s_barrier
	s_add_i32 s73, s73, s0
	v_lshl_add_u64 v[210:211], s[30:31], 0, v[152:153]
	s_mov_b32 m0, s73
	ds_read_b128 v[174:177], v225 offset:16384
	ds_read_b128 v[178:181], v225 offset:17408
	ds_read_b128 v[182:185], v225 offset:18432
	ds_read_b128 v[190:193], v225 offset:19456
	ds_read_b128 v[194:197], v225 offset:20480
	ds_read_b128 v[198:201], v225 offset:21504
	ds_read_b128 v[202:205], v225 offset:22528
	ds_read_b128 v[206:209], v225 offset:23552
	global_load_lds_dwordx4 v[210:211], off
	s_add_i32 m0, s73, 0x2000
	s_add_u32 s82, s30, 0x100000
	v_lshl_add_u64 v[212:213], s[30:31], 0, v[156:157]
	s_addc_u32 s83, s31, 0
	s_add_i32 s73, s75, s0
	global_load_lds_dwordx4 v[212:213], off
	v_lshl_add_u64 v[214:215], s[82:83], 0, v[152:153]
	s_mov_b32 m0, s73
	v_lshl_add_u64 v[216:217], s[66:67], 0, v[154:155]
	global_load_lds_dwordx4 v[214:215], off
	v_lshl_add_u64 v[214:215], s[82:83], 0, v[156:157]
	s_add_i32 m0, s73, 0x2000
	s_nop 0
	global_load_lds_dwordx4 v[214:215], off
	v_lshl_add_u64 v[214:215], s[66:67], 0, v[150:151]
	s_mov_b32 m0, s1
	s_nop 0
	global_load_lds_dwordx4 v[214:215], off
	s_mov_b32 m0, s10
	s_nop 0
	global_load_lds_dwordx4 v[216:217], off
	s_waitcnt vmcnt(8)
	s_waitcnt lgkmcnt(0)
	s_barrier
	s_setprio 1
	v_mfma_f32_16x16x32_bf16 v[94:97], v[98:101], v[174:177], v[94:97]
	v_mfma_f32_16x16x32_bf16 v[90:93], v[106:109], v[174:177], v[90:93]
	v_mfma_f32_16x16x32_bf16 v[86:89], v[98:101], v[182:185], v[86:89]
	v_mfma_f32_16x16x32_bf16 v[82:85], v[106:109], v[182:185], v[82:85]
	v_mfma_f32_16x16x32_bf16 v[78:81], v[98:101], v[194:197], v[78:81]
	v_mfma_f32_16x16x32_bf16 v[74:77], v[106:109], v[194:197], v[74:77]
	v_mfma_f32_16x16x32_bf16 v[70:73], v[98:101], v[202:205], v[70:73]
	v_mfma_f32_16x16x32_bf16 v[66:69], v[106:109], v[202:205], v[66:69]
	v_mfma_f32_16x16x32_bf16 v[94:97], v[102:105], v[178:181], v[94:97]
	v_mfma_f32_16x16x32_bf16 v[90:93], v[110:113], v[178:181], v[90:93]
	v_mfma_f32_16x16x32_bf16 v[86:89], v[102:105], v[190:193], v[86:89]
	v_mfma_f32_16x16x32_bf16 v[82:85], v[110:113], v[190:193], v[82:85]
	v_mfma_f32_16x16x32_bf16 v[78:81], v[102:105], v[198:201], v[78:81]
	v_mfma_f32_16x16x32_bf16 v[74:77], v[110:113], v[198:201], v[74:77]
	v_mfma_f32_16x16x32_bf16 v[70:73], v[102:105], v[206:209], v[70:73]
	v_mfma_f32_16x16x32_bf16 v[66:69], v[110:113], v[206:209], v[66:69]
	v_mfma_f32_16x16x32_bf16 v[28:31], v[146:149], v[174:177], v[28:31]
	v_mfma_f32_16x16x32_bf16 v[24:27], v[166:169], v[174:177], v[24:27]
	v_mfma_f32_16x16x32_bf16 v[20:23], v[146:149], v[182:185], v[20:23]
	v_mfma_f32_16x16x32_bf16 v[16:19], v[166:169], v[182:185], v[16:19]
	v_mfma_f32_16x16x32_bf16 v[12:15], v[146:149], v[194:197], v[12:15]
	v_mfma_f32_16x16x32_bf16 v[8:11], v[166:169], v[194:197], v[8:11]
	v_mfma_f32_16x16x32_bf16 v[4:7], v[146:149], v[202:205], v[4:7]
	v_mfma_f32_16x16x32_bf16 v[0:3], v[166:169], v[202:205], v[0:3]
	v_mfma_f32_16x16x32_bf16 v[28:31], v[162:165], v[178:181], v[28:31]
	v_mfma_f32_16x16x32_bf16 v[24:27], v[170:173], v[178:181], v[24:27]
	v_mfma_f32_16x16x32_bf16 v[20:23], v[162:165], v[190:193], v[20:23]
	v_mfma_f32_16x16x32_bf16 v[16:19], v[170:173], v[190:193], v[16:19]
	v_mfma_f32_16x16x32_bf16 v[12:15], v[162:165], v[198:201], v[12:15]
	v_mfma_f32_16x16x32_bf16 v[8:11], v[170:173], v[198:201], v[8:11]
	v_mfma_f32_16x16x32_bf16 v[4:7], v[162:165], v[206:209], v[4:7]
	v_mfma_f32_16x16x32_bf16 v[0:3], v[170:173], v[206:209], v[0:3]
	s_setprio 0
	s_barrier
	s_add_i32 s73, 0, 0x18000
	s_add_i32 s75, 0, 0x1c000
	v_add_u32_e32 v110, s73, v223
	v_add_u32_e32 v170, s75, v223
	ds_read_b128 v[98:101], v110
	ds_read_b128 v[102:105], v110 offset:1024
	ds_read_b128 v[106:109], v110 offset:2048
	ds_read_b128 v[110:113], v110 offset:3072
	ds_read_b128 v[146:149], v170
	ds_read_b128 v[162:165], v170 offset:1024
	ds_read_b128 v[166:169], v170 offset:2048
	ds_read_b128 v[170:173], v170 offset:3072
	s_add_u32 s66, s66, 0x100000
	s_addc_u32 s67, s67, 0
	s_mov_b32 m0, s11
	v_lshl_add_u64 v[218:219], s[66:67], 0, v[150:151]
	ds_read_b128 v[174:177], v225 offset:32768
	ds_read_b128 v[178:181], v225 offset:33792
	ds_read_b128 v[182:185], v225 offset:34816
	ds_read_b128 v[190:193], v225 offset:35840
	ds_read_b128 v[194:197], v225 offset:36864
	ds_read_b128 v[198:201], v225 offset:37888
	ds_read_b128 v[202:205], v225 offset:38912
	ds_read_b128 v[206:209], v225 offset:39936
	global_load_lds_dwordx4 v[218:219], off
	v_lshl_add_u64 v[218:219], s[66:67], 0, v[154:155]
	s_mov_b32 m0, s13
	s_nop 0
	global_load_lds_dwordx4 v[218:219], off
	s_waitcnt vmcnt(8)
	s_waitcnt lgkmcnt(0)
	s_barrier
	s_setprio 1
	v_mfma_f32_16x16x32_bf16 v[142:145], v[98:101], v[174:177], v[142:145]
	v_mfma_f32_16x16x32_bf16 v[138:141], v[106:109], v[174:177], v[138:141]
	v_mfma_f32_16x16x32_bf16 v[134:137], v[98:101], v[182:185], v[134:137]
	v_mfma_f32_16x16x32_bf16 v[130:133], v[106:109], v[182:185], v[130:133]
	v_mfma_f32_16x16x32_bf16 v[126:129], v[98:101], v[194:197], v[126:129]
	v_mfma_f32_16x16x32_bf16 v[122:125], v[106:109], v[194:197], v[122:125]
	v_mfma_f32_16x16x32_bf16 v[118:121], v[98:101], v[202:205], v[118:121]
	v_mfma_f32_16x16x32_bf16 v[114:117], v[106:109], v[202:205], v[114:117]
	v_mfma_f32_16x16x32_bf16 v[142:145], v[102:105], v[178:181], v[142:145]
	v_mfma_f32_16x16x32_bf16 v[138:141], v[110:113], v[178:181], v[138:141]
	v_mfma_f32_16x16x32_bf16 v[134:137], v[102:105], v[190:193], v[134:137]
	v_mfma_f32_16x16x32_bf16 v[130:133], v[110:113], v[190:193], v[130:133]
	v_mfma_f32_16x16x32_bf16 v[126:129], v[102:105], v[198:201], v[126:129]
	v_mfma_f32_16x16x32_bf16 v[122:125], v[110:113], v[198:201], v[122:125]
	v_mfma_f32_16x16x32_bf16 v[118:121], v[102:105], v[206:209], v[118:121]
	v_mfma_f32_16x16x32_bf16 v[114:117], v[110:113], v[206:209], v[114:117]
	v_mfma_f32_16x16x32_bf16 v[60:63], v[146:149], v[174:177], v[60:63]
	v_mfma_f32_16x16x32_bf16 v[56:59], v[166:169], v[174:177], v[56:59]
	v_mfma_f32_16x16x32_bf16 v[52:55], v[146:149], v[182:185], v[52:55]
	v_mfma_f32_16x16x32_bf16 v[48:51], v[166:169], v[182:185], v[48:51]
	v_mfma_f32_16x16x32_bf16 v[44:47], v[146:149], v[194:197], v[44:47]
	v_mfma_f32_16x16x32_bf16 v[40:43], v[166:169], v[194:197], v[40:43]
	v_mfma_f32_16x16x32_bf16 v[36:39], v[146:149], v[202:205], v[36:39]
	v_mfma_f32_16x16x32_bf16 v[32:35], v[166:169], v[202:205], v[32:35]
	v_mfma_f32_16x16x32_bf16 v[60:63], v[162:165], v[178:181], v[60:63]
	v_mfma_f32_16x16x32_bf16 v[56:59], v[170:173], v[178:181], v[56:59]
	v_mfma_f32_16x16x32_bf16 v[52:55], v[162:165], v[190:193], v[52:55]
	v_mfma_f32_16x16x32_bf16 v[48:51], v[170:173], v[190:193], v[48:51]
	v_mfma_f32_16x16x32_bf16 v[44:47], v[162:165], v[198:201], v[44:47]
	v_mfma_f32_16x16x32_bf16 v[40:43], v[170:173], v[198:201], v[40:43]
	v_mfma_f32_16x16x32_bf16 v[36:39], v[162:165], v[206:209], v[36:39]
	v_mfma_f32_16x16x32_bf16 v[32:35], v[170:173], v[206:209], v[32:35]
	s_setprio 0
	s_barrier
	s_add_i32 s66, s73, s0
	v_lshl_add_u64 v[210:211], v[210:211], 0, s[16:17]
	s_mov_b32 m0, s66
	ds_read_b128 v[174:177], v225 offset:49152
	ds_read_b128 v[178:181], v225 offset:50176
	ds_read_b128 v[182:185], v225 offset:51200
	ds_read_b128 v[190:193], v225 offset:52224
	ds_read_b128 v[194:197], v225 offset:53248
	ds_read_b128 v[198:201], v225 offset:54272
	ds_read_b128 v[202:205], v225 offset:55296
	ds_read_b128 v[206:209], v225 offset:56320
	global_load_lds_dwordx4 v[210:211], off
	s_add_i32 m0, s66, 0x2000
	s_add_u32 s30, s30, 0x100080
	v_lshl_add_u64 v[210:211], v[212:213], 0, s[16:17]
	s_addc_u32 s31, s31, 0
	s_add_i32 s66, s75, s0
	global_load_lds_dwordx4 v[210:211], off
	v_lshl_add_u64 v[210:211], s[30:31], 0, v[152:153]
	s_mov_b32 m0, s66
	s_nop 0
	global_load_lds_dwordx4 v[210:211], off
	v_lshl_add_u64 v[210:211], s[30:31], 0, v[156:157]
	s_add_i32 m0, s66, 0x2000
	s_nop 0
	global_load_lds_dwordx4 v[210:211], off
	v_lshl_add_u64 v[210:211], v[214:215], 0, s[16:17]
	s_mov_b32 m0, s4
	s_nop 0
	global_load_lds_dwordx4 v[210:211], off
	v_lshl_add_u64 v[210:211], v[216:217], 0, s[16:17]
	s_mov_b32 m0, s90
	s_nop 0
	global_load_lds_dwordx4 v[210:211], off
	s_waitcnt vmcnt(8)
	s_waitcnt lgkmcnt(0)
	s_barrier
	s_setprio 1
	v_mfma_f32_16x16x32_bf16 v[94:97], v[98:101], v[174:177], v[94:97]
	v_mfma_f32_16x16x32_bf16 v[90:93], v[106:109], v[174:177], v[90:93]
	v_mfma_f32_16x16x32_bf16 v[86:89], v[98:101], v[182:185], v[86:89]
	v_mfma_f32_16x16x32_bf16 v[82:85], v[106:109], v[182:185], v[82:85]
	v_mfma_f32_16x16x32_bf16 v[78:81], v[98:101], v[194:197], v[78:81]
	v_mfma_f32_16x16x32_bf16 v[74:77], v[106:109], v[194:197], v[74:77]
	v_mfma_f32_16x16x32_bf16 v[70:73], v[98:101], v[202:205], v[70:73]
	v_mfma_f32_16x16x32_bf16 v[66:69], v[106:109], v[202:205], v[66:69]
	v_mfma_f32_16x16x32_bf16 v[94:97], v[102:105], v[178:181], v[94:97]
	v_mfma_f32_16x16x32_bf16 v[90:93], v[110:113], v[178:181], v[90:93]
	v_mfma_f32_16x16x32_bf16 v[86:89], v[102:105], v[190:193], v[86:89]
	v_mfma_f32_16x16x32_bf16 v[82:85], v[110:113], v[190:193], v[82:85]
	v_mfma_f32_16x16x32_bf16 v[78:81], v[102:105], v[198:201], v[78:81]
	v_mfma_f32_16x16x32_bf16 v[74:77], v[110:113], v[198:201], v[74:77]
	v_mfma_f32_16x16x32_bf16 v[70:73], v[102:105], v[206:209], v[70:73]
	v_mfma_f32_16x16x32_bf16 v[66:69], v[110:113], v[206:209], v[66:69]
	v_mfma_f32_16x16x32_bf16 v[28:31], v[146:149], v[174:177], v[28:31]
	v_mfma_f32_16x16x32_bf16 v[24:27], v[166:169], v[174:177], v[24:27]
	v_mfma_f32_16x16x32_bf16 v[20:23], v[146:149], v[182:185], v[20:23]
	v_mfma_f32_16x16x32_bf16 v[16:19], v[166:169], v[182:185], v[16:19]
	v_mfma_f32_16x16x32_bf16 v[12:15], v[146:149], v[194:197], v[12:15]
	v_mfma_f32_16x16x32_bf16 v[8:11], v[166:169], v[194:197], v[8:11]
	v_mfma_f32_16x16x32_bf16 v[4:7], v[146:149], v[202:205], v[4:7]
	v_mfma_f32_16x16x32_bf16 v[0:3], v[166:169], v[202:205], v[0:3]
	v_mfma_f32_16x16x32_bf16 v[28:31], v[162:165], v[178:181], v[28:31]
	v_mfma_f32_16x16x32_bf16 v[24:27], v[170:173], v[178:181], v[24:27]
	v_mfma_f32_16x16x32_bf16 v[20:23], v[162:165], v[190:193], v[20:23]
	v_mfma_f32_16x16x32_bf16 v[16:19], v[170:173], v[190:193], v[16:19]
	v_mfma_f32_16x16x32_bf16 v[12:15], v[162:165], v[198:201], v[12:15]
	v_mfma_f32_16x16x32_bf16 v[8:11], v[170:173], v[198:201], v[8:11]
	v_mfma_f32_16x16x32_bf16 v[4:7], v[162:165], v[206:209], v[4:7]
	v_mfma_f32_16x16x32_bf16 v[0:3], v[170:173], v[206:209], v[0:3]
	s_setprio 0
	s_add_i32 s72, s72, 2
	s_add_u32 s28, s28, 0x100
	s_addc_u32 s29, s29, 0
	s_add_u32 s70, s70, 0x100
	s_addc_u32 s71, s71, 0
	s_cmp_gt_u32 s72, 61
	s_barrier
	s_cbranch_scc0 .LBB0_1532
	s_and_b64 vcc, exec, s[44:45]
	s_cbranch_vccz .LBB0_1535
	s_barrier
